# GEMM tile loops: priority 3 kept from the DMA issue through the fragment ds_read issue (MFMA block stays at 1)
# baseline (speedup 1.0000x reference)
; __device__ __forceinline__ void gemm_mainloop_d(const bf16_t* __restrict__ Ap, int lda, const bf16_t* __restrict__ Bt, int K,
;                                                 int m0, int n0, f32x4 (&acc)[4][4], char* lds) {
;     ...
;   auto dma = [&](int kt, int st) {
;     char* la = lds + st * 32768; char* lb = la + 16384;
; #pragma unroll
;     for (int i = 0; i < 4; i++) {
;       const int row = i * 32 + lrow; const int c = cph ^ ((row >> 1) & 7);
;       __builtin_amdgcn_global_load_lds((const unsigned*)(Ap + (size_t)(m0 + row) * lda + kt * 64 + c * 8), (__attribute__((address_space(3))) unsigned*)(la + i * 4096 + tid * 16), 16, 0, 0);
;       __builtin_amdgcn_global_load_lds((const unsigned*)(Bt + (size_t)(n0 + row) * K + kt * 64 + c * 8), (__attribute__((address_space(3))) unsigned*)(lb + i * 4096 + tid * 16), 16, 0, 0);
;     }
;   };
;   dma(0, 0);
;   asm volatile("s_waitcnt vmcnt(0)" ::: "memory"); __builtin_amdgcn_s_barrier(); asm volatile("" ::: "memory");
;   for (int kt = 0; kt < nk; kt++) {
;     const int st = kt & 1;
;     if (kt + 1 < nk) dma(kt + 1, st ^ 1);
;     const char* la = lds + st * 32768; const char* lb = la + 16384;
;     bf16x8 af[2][4], bfv[2][4];
; #pragma unroll
;     for (int kc = 0; kc < 2; kc++) {
; #pragma unroll
;       for (int m = 0; m < 4; m++) { const int row = wr * 64 + m * 16 + fr; af[kc][m] = *(const bf16x8*)(la + (row * 8 + ((kc * 4 + fq) ^ ((row >> 1) & 7))) * 16); }
; #pragma unroll
;       for (int n = 0; n < 4; n++) { const int row = wc * 64 + n * 16 + fr; bfv[kc][n] = *(const bf16x8*)(lb + (row * 8 + ((kc * 4 + fq) ^ ((row >> 1) & 7))) * 16); }
;     }
;     __builtin_amdgcn_s_setprio(1);
; #pragma unroll
;     for (int kc = 0; kc < 2; kc++)
; #pragma unroll
;       for (int m = 0; m < 4; m++)
; #pragma unroll
;         for (int n = 0; n < 4; n++) acc[m][n] = __builtin_amdgcn_mfma_f32_16x16x32_bf16(bfv[kc][n], af[kc][m], acc[m][n], 0, 0, 0);
;     __builtin_amdgcn_s_setprio(0);
;     asm volatile("s_waitcnt vmcnt(0) lgkmcnt(0)" ::: "memory"); __builtin_amdgcn_s_barrier(); asm volatile("" ::: "memory");
;   }
.LBB0_95:
	s_setprio 3
	s_and_b32 s29, s26, 0x8000
	s_xor_b32 s37, s29, 0x8000
	s_add_i32 s37, s37, vcc_hi
	s_mov_b32 m0, s37
	s_add_i32 vcc_lo, s37, 0x4000
	global_load_lds_dwordx4 v150, s[46:47]
	s_mov_b32 m0, vcc_lo
	s_add_i32 vcc_lo, s37, 0x1000
	global_load_lds_dwordx4 v151, s[46:47]
	s_mov_b32 m0, vcc_lo
	s_add_i32 vcc_lo, s37, 0x5000
	global_load_lds_dwordx4 v152, s[46:47]
	s_mov_b32 m0, vcc_lo
	s_add_i32 vcc_lo, s37, 0x2000
	global_load_lds_dwordx4 v153, s[46:47]
	s_mov_b32 m0, vcc_lo
	s_add_i32 vcc_lo, s37, 0x6000
	global_load_lds_dwordx4 v154, s[46:47]
	s_mov_b32 m0, vcc_lo
	s_add_i32 vcc_lo, s37, 0x3000
	global_load_lds_dwordx4 v155, s[46:47]
	s_mov_b32 m0, vcc_lo
	s_add_i32 vcc_lo, s37, 0x7000
	global_load_lds_dwordx4 v156, s[46:47]
	s_mov_b32 m0, vcc_lo
	s_nop 0
	global_load_lds_dwordx4 v157, s[46:47]
	v_add_u32_e32 v150, 0x80, v150
	v_add_u32_e32 v151, 0x80, v151
	v_add_u32_e32 v152, 0x80, v152
	v_add_u32_e32 v153, 0x80, v153
	v_add_u32_e32 v154, 0x80, v154
	v_add_u32_e32 v155, 0x80, v155
	v_add_u32_e32 v156, 0x80, v156
	v_add_u32_e32 v157, 0x80, v157
	v_add_u32_e32 v98, s29, v85
	v_add_u32_e32 v114, s29, v84
	v_add_u32_e32 v130, s29, v83
	v_add_u32_e32 v146, s29, v2
	ds_read_b128 v[86:89], v98
	ds_read_b128 v[90:93], v98 offset:2048
	ds_read_b128 v[94:97], v98 offset:4096
	ds_read_b128 v[98:101], v98 offset:6144
	ds_read_b128 v[102:105], v114 offset:16384
	ds_read_b128 v[106:109], v114 offset:18432
	ds_read_b128 v[110:113], v114 offset:20480
	ds_read_b128 v[114:117], v114 offset:22528
	ds_read_b128 v[118:121], v130
	ds_read_b128 v[122:125], v130 offset:2048
	ds_read_b128 v[126:129], v130 offset:4096
	ds_read_b128 v[130:133], v130 offset:6144
	ds_read_b128 v[134:137], v146 offset:16384
	ds_read_b128 v[138:141], v146 offset:18432
	ds_read_b128 v[142:145], v146 offset:20480
	ds_read_b128 v[146:149], v146 offset:22528
	s_setprio 1
	s_waitcnt lgkmcnt(0)
	v_mfma_f32_16x16x32_bf16 v[64:67], v[102:105], v[86:89], v[64:67]
	v_mfma_f32_16x16x32_bf16 v[60:63], v[106:109], v[86:89], v[60:63]
	v_mfma_f32_16x16x32_bf16 v[56:59], v[110:113], v[86:89], v[56:59]
	v_mfma_f32_16x16x32_bf16 v[52:55], v[114:117], v[86:89], v[52:55]
	v_mfma_f32_16x16x32_bf16 v[48:51], v[102:105], v[90:93], v[48:51]
	v_mfma_f32_16x16x32_bf16 v[44:47], v[106:109], v[90:93], v[44:47]
	v_mfma_f32_16x16x32_bf16 v[40:43], v[110:113], v[90:93], v[40:43]
	v_mfma_f32_16x16x32_bf16 v[36:39], v[114:117], v[90:93], v[36:39]
	v_mfma_f32_16x16x32_bf16 v[32:35], v[102:105], v[94:97], v[32:35]
	v_mfma_f32_16x16x32_bf16 v[28:31], v[106:109], v[94:97], v[28:31]
	v_mfma_f32_16x16x32_bf16 v[24:27], v[110:113], v[94:97], v[24:27]
	v_mfma_f32_16x16x32_bf16 v[20:23], v[114:117], v[94:97], v[20:23]
	v_mfma_f32_16x16x32_bf16 v[16:19], v[102:105], v[98:101], v[16:19]
	v_mfma_f32_16x16x32_bf16 v[12:15], v[106:109], v[98:101], v[12:15]
	v_mfma_f32_16x16x32_bf16 v[8:11], v[110:113], v[98:101], v[8:11]
	v_mfma_f32_16x16x32_bf16 v[4:7], v[114:117], v[98:101], v[4:7]
	v_mfma_f32_16x16x32_bf16 v[64:67], v[134:137], v[118:121], v[64:67]
	v_mfma_f32_16x16x32_bf16 v[60:63], v[138:141], v[118:121], v[60:63]
	v_mfma_f32_16x16x32_bf16 v[56:59], v[142:145], v[118:121], v[56:59]
	v_mfma_f32_16x16x32_bf16 v[52:55], v[146:149], v[118:121], v[52:55]
	v_mfma_f32_16x16x32_bf16 v[48:51], v[134:137], v[122:125], v[48:51]
	v_mfma_f32_16x16x32_bf16 v[44:47], v[138:141], v[122:125], v[44:47]
	v_mfma_f32_16x16x32_bf16 v[40:43], v[142:145], v[122:125], v[40:43]
	v_mfma_f32_16x16x32_bf16 v[36:39], v[146:149], v[122:125], v[36:39]
	v_mfma_f32_16x16x32_bf16 v[32:35], v[134:137], v[126:129], v[32:35]
	v_mfma_f32_16x16x32_bf16 v[28:31], v[138:141], v[126:129], v[28:31]
	v_mfma_f32_16x16x32_bf16 v[24:27], v[142:145], v[126:129], v[24:27]
	v_mfma_f32_16x16x32_bf16 v[20:23], v[146:149], v[126:129], v[20:23]
	v_mfma_f32_16x16x32_bf16 v[16:19], v[134:137], v[130:133], v[16:19]
	v_mfma_f32_16x16x32_bf16 v[12:15], v[138:141], v[130:133], v[12:15]
	v_mfma_f32_16x16x32_bf16 v[8:11], v[142:145], v[130:133], v[8:11]
	v_mfma_f32_16x16x32_bf16 v[4:7], v[146:149], v[130:133], v[4:7]
	s_setprio 0
	s_waitcnt vmcnt(0) lgkmcnt(0)
	s_barrier
	s_add_u32 s24, s24, 0x80
	s_addc_u32 s25, s25, 0
	s_add_i32 s26, s26, 0x8000
	s_cmpk_eq_i32 s24, 0x1580
	s_cbranch_scc0 .LBB0_95
; __device__ __forceinline__ void gemm_mainloop_d(const bf16_t* __restrict__ Ap, int lda, const bf16_t* __restrict__ Bt, int K,
;                                                 int m0, int n0, f32x4 (&acc)[4][4], char* lds) {
;     ...
;     const char* la = lds + st * 32768; const char* lb = la + 16384;
;     bf16x8 af[2][4], bfv[2][4];
; #pragma unroll
;     for (int kc = 0; kc < 2; kc++) {
; #pragma unroll
;       for (int m = 0; m < 4; m++) { const int row = wr * 64 + m * 16 + fr; af[kc][m] = *(const bf16x8*)(la + (row * 8 + ((kc * 4 + fq) ^ ((row >> 1) & 7))) * 16); }
; #pragma unroll
;       for (int n = 0; n < 4; n++) { const int row = wc * 64 + n * 16 + fr; bfv[kc][n] = *(const bf16x8*)(lb + (row * 8 + ((kc * 4 + fq) ^ ((row >> 1) & 7))) * 16); }
;     }
;     __builtin_amdgcn_s_setprio(1);
; #pragma unroll
;     for (int kc = 0; kc < 2; kc++)
; #pragma unroll
;       for (int m = 0; m < 4; m++)
; #pragma unroll
;         for (int n = 0; n < 4; n++) acc[m][n] = __builtin_amdgcn_mfma_f32_16x16x32_bf16(bfv[kc][n], af[kc][m], acc[m][n], 0, 0, 0);
;     __builtin_amdgcn_s_setprio(0);
;     asm volatile("s_waitcnt vmcnt(0) lgkmcnt(0)" ::: "memory"); __builtin_amdgcn_s_barrier(); asm volatile("" ::: "memory");
;   }
	v_add_u32_e32 v0, 0, v85
	ds_read_b128 v[68:71], v0 offset:32768
	ds_read_b128 v[72:75], v0 offset:34816
	ds_read_b128 v[76:79], v0 offset:36864
	ds_read_b128 v[86:89], v0 offset:38912
	v_add_u32_e32 v0, 0, v84
	ds_read_b128 v[90:93], v0 offset:49152
	ds_read_b128 v[94:97], v0 offset:51200
	ds_read_b128 v[98:101], v0 offset:53248
	ds_read_b128 v[102:105], v0 offset:55296
	v_add_u32_e32 v0, 0, v83
	s_add_u32 s24, s46, s27
	ds_read_b128 v[80:83], v0 offset:32768
	ds_read_b128 v[106:109], v0 offset:34816
	ds_read_b128 v[110:113], v0 offset:36864
	ds_read_b128 v[114:117], v0 offset:38912
	v_add_u32_e32 v0, 0, v2
	s_addc_u32 s25, s47, 0
	ds_read_b128 v[118:121], v0 offset:49152
	ds_read_b128 v[122:125], v0 offset:51200
	ds_read_b128 v[126:129], v0 offset:53248
	ds_read_b128 v[130:133], v0 offset:55296
	s_add_u32 s28, s46, s28
	s_addc_u32 s29, s47, 0
	s_add_u32 s26, s24, 0x65a8000
	s_addc_u32 s27, s25, 0
	s_add_u32 s24, s28, 0xff8c000
	s_addc_u32 s25, s29, 0
	s_setprio 1
	s_waitcnt lgkmcnt(0)
	v_mfma_f32_16x16x32_bf16 v[56:59], v[98:101], v[68:71], v[56:59]
	v_mfma_f32_16x16x32_bf16 v[48:51], v[90:93], v[72:75], v[48:51]
	v_mfma_f32_16x16x32_bf16 v[44:47], v[94:97], v[72:75], v[44:47]
	v_mfma_f32_16x16x32_bf16 v[40:43], v[98:101], v[72:75], v[40:43]
	v_mfma_f32_16x16x32_bf16 v[36:39], v[102:105], v[72:75], v[36:39]
	v_mfma_f32_16x16x32_bf16 v[32:35], v[90:93], v[76:79], v[32:35]
	v_mfma_f32_16x16x32_bf16 v[28:31], v[94:97], v[76:79], v[28:31]
	v_mfma_f32_16x16x32_bf16 v[24:27], v[98:101], v[76:79], v[24:27]
	v_mfma_f32_16x16x32_bf16 v[20:23], v[102:105], v[76:79], v[20:23]
	v_mfma_f32_16x16x32_bf16 v[16:19], v[90:93], v[86:89], v[16:19]
	v_mfma_f32_16x16x32_bf16 v[12:15], v[94:97], v[86:89], v[12:15]
	v_mfma_f32_16x16x32_bf16 v[8:11], v[98:101], v[86:89], v[8:11]
	v_mfma_f32_16x16x32_bf16 v[4:7], v[102:105], v[86:89], v[4:7]
	v_mfma_f32_16x16x32_bf16 v[64:67], v[90:93], v[68:71], v[64:67]
	v_mfma_f32_16x16x32_bf16 v[60:63], v[94:97], v[68:71], v[60:63]
	v_mfma_f32_16x16x32_bf16 v[52:55], v[102:105], v[68:71], v[52:55]
	v_mfma_f32_16x16x32_bf16 v[56:59], v[126:129], v[80:83], v[56:59]
	v_mfma_f32_16x16x32_bf16 v[48:51], v[118:121], v[106:109], v[48:51]
	v_mfma_f32_16x16x32_bf16 v[44:47], v[122:125], v[106:109], v[44:47]
	v_mfma_f32_16x16x32_bf16 v[40:43], v[126:129], v[106:109], v[40:43]
	v_mfma_f32_16x16x32_bf16 v[36:39], v[130:133], v[106:109], v[36:39]
	v_mfma_f32_16x16x32_bf16 v[32:35], v[118:121], v[110:113], v[32:35]
	v_mfma_f32_16x16x32_bf16 v[28:31], v[122:125], v[110:113], v[28:31]
	v_mfma_f32_16x16x32_bf16 v[24:27], v[126:129], v[110:113], v[24:27]
	v_mfma_f32_16x16x32_bf16 v[20:23], v[130:133], v[110:113], v[20:23]
	v_mfma_f32_16x16x32_bf16 v[16:19], v[118:121], v[114:117], v[16:19]
	v_mfma_f32_16x16x32_bf16 v[12:15], v[122:125], v[114:117], v[12:15]
	v_mfma_f32_16x16x32_bf16 v[8:11], v[126:129], v[114:117], v[8:11]
	v_mfma_f32_16x16x32_bf16 v[4:7], v[130:133], v[114:117], v[4:7]
	v_mfma_f32_16x16x32_bf16 v[64:67], v[118:121], v[80:83], v[64:67]
	v_mfma_f32_16x16x32_bf16 v[60:63], v[122:125], v[80:83], v[60:63]
	v_mfma_f32_16x16x32_bf16 v[68:71], v[130:133], v[80:83], v[52:55]
	s_setprio 0
	v_mov_b32_e32 v0, v198
	s_waitcnt vmcnt(0) lgkmcnt(0)
	s_barrier
; __device__ __forceinline__ unsigned pk2(float lo, float hi) { unsigned r; asm("v_cvt_pk_bf16_f32 %0, %1, %2" : "=v"(r) : "v"(lo), "v"(hi)); return r; }
; __device__ __forceinline__ float bflo(unsigned u) { return __uint_as_float(u << 16); }
; __device__ __forceinline__ float bfhi(unsigned u) { return __uint_as_float(u & 0xffff0000u); }
; __device__ __forceinline__ void gemm_RES(const bf16_t* A, int K, const bf16_t* Bt, const float* xin, float* xout, bf16_t* xb, float* rss, int item, char* lds) {
;     ...
; #pragma unroll
;   for (int m = 0; m < 4; m++) {
;     const int rowg = m0 + wr * 64 + m * 16 + fr;
;     const size_t ro = (size_t)rowg * DM;
;     float sq = 0.f;
; #pragma unroll
;     for (int n = 0; n < 4; n++) {
;       const int col = n0 + wc * 64 + n * 16 + fq * 4;
;       f32x4 xv = *(const f32x4*)(xin + ro + col);
;       const f32x4 xn = xv + acc[m][n];
;       *(f32x4*)(xout + ro + col) = xn;
;       u32x2 w; w[0] = pk2(xn[0], xn[1]); w[1] = pk2(xn[2], xn[3]); *(u32x2*)(xb + ro + col) = w;
;       const float b0 = bflo(w[0]), b1 = bfhi(w[0]), b2 = bflo(w[1]), b3 = bfhi(w[1]);
;       sq += b0 * b0 + b1 * b1 + b2 * b2 + b3 * b3;
;     }
;     sq += __shfl_xor(sq, 16); sq += __shfl_xor(sq, 32);
;     if (fq == 0) unsafeAtomicAdd(rss + rowg, sq);
;   }
	v_readlane_b32 s4, v252, 35
	v_ashrrev_i32_e32 v2, 1, v0
	v_and_b32_e32 v2, 0xffffffc0, v2
	v_bfe_u32 v80, v0, 4, 2
	v_add_u32_e32 v2, s3, v2
	v_and_b32_e32 v1, 64, v0
	v_and_or_b32 v0, v0, 15, v2
	v_lshlrev_b32_e32 v2, 2, v80
	v_or3_b32 v54, v2, v1, s2
	v_ashrrev_i32_e32 v1, 31, v0
	v_lshlrev_b64 v[52:53], 12, v[0:1]
	v_readlane_b32 s18, v252, 49
	v_readlane_b32 s19, v252, 50
	v_lshlrev_b32_e32 v2, 2, v54
	v_readlane_b32 s5, v252, 36
	v_lshl_add_u64 v[52:53], s[18:19], 0, v[52:53]
	v_lshl_add_u64 v[76:77], v[52:53], 0, v[2:3]
	global_load_dwordx4 v[72:75], v[76:77], off
	v_lshlrev_b32_e32 v52, 1, v54
	v_lshlrev_b64 v[54:55], 11, v[0:1]
	v_mov_b32_e32 v53, v3
	v_lshl_add_u64 v[54:55], s[26:27], 0, v[54:55]
	v_lshl_add_u64 v[78:79], v[54:55], 0, v[52:53]
	v_readlane_b32 s6, v252, 37
	v_readlane_b32 s7, v252, 38
	v_readlane_b32 s8, v252, 39
	v_readlane_b32 s9, v252, 40
	v_readlane_b32 s10, v252, 41
	v_readlane_b32 s11, v252, 42
	v_readlane_b32 s12, v252, 43
	v_readlane_b32 s13, v252, 44
	v_readlane_b32 s14, v252, 45
	v_readlane_b32 s15, v252, 46
	v_readlane_b32 s16, v252, 47
	v_readlane_b32 s17, v252, 48
	s_waitcnt vmcnt(0)
	v_pk_add_f32 v[66:67], v[66:67], v[74:75]
	v_pk_add_f32 v[64:65], v[64:65], v[72:73]
	global_store_dwordx4 v[76:77], v[64:67], off
	v_cvt_pk_bf16_f32 v54, v64, v65
	v_cvt_pk_bf16_f32 v55, v66, v67
	global_store_dwordx2 v[78:79], v[54:55], off
	global_load_dwordx4 v[64:67], v[76:77], off offset:64
	s_waitcnt vmcnt(0)
	v_pk_add_f32 v[62:63], v[62:63], v[66:67]
	v_pk_add_f32 v[60:61], v[60:61], v[64:65]
	global_store_dwordx4 v[76:77], v[60:63], off offset:64
	v_cvt_pk_bf16_f32 v64, v60, v61
	v_cvt_pk_bf16_f32 v65, v62, v63
	global_store_dwordx2 v[78:79], v[64:65], off offset:32
	global_load_dwordx4 v[60:63], v[76:77], off offset:128
	v_lshlrev_b32_e32 v66, 16, v54
	v_and_b32_e32 v54, 0xffff0000, v54
	v_mul_f32_e32 v54, v54, v54
	v_lshlrev_b32_e32 v67, 16, v55
	v_fmac_f32_e32 v54, v66, v66
	v_and_b32_e32 v55, 0xffff0000, v55
	v_fmac_f32_e32 v54, v67, v67
	v_fmac_f32_e32 v54, v55, v55
	v_lshlrev_b32_e32 v55, 16, v64
	v_and_b32_e32 v64, 0xffff0000, v64
	v_mul_f32_e32 v64, v64, v64
	v_lshlrev_b32_e32 v66, 16, v65
	v_fmac_f32_e32 v64, v55, v55
	v_and_b32_e32 v65, 0xffff0000, v65
	v_fmac_f32_e32 v64, v66, v66
	v_fmac_f32_e32 v64, v65, v65
	v_add_f32_e32 v54, v54, v64
	s_waitcnt vmcnt(0)
	v_pk_add_f32 v[58:59], v[58:59], v[62:63]
	v_pk_add_f32 v[56:57], v[56:57], v[60:61]
	global_store_dwordx4 v[76:77], v[56:59], off offset:128
	v_cvt_pk_bf16_f32 v62, v56, v57
	v_cvt_pk_bf16_f32 v63, v58, v59
	global_store_dwordx2 v[78:79], v[62:63], off offset:64
	global_load_dwordx4 v[58:61], v[76:77], off offset:192
	v_lshlrev_b32_e32 v55, 16, v62
	v_and_b32_e32 v62, 0xffff0000, v62
	v_mul_f32_e32 v62, v62, v62
	v_lshlrev_b32_e32 v64, 16, v63
	v_fmac_f32_e32 v62, v55, v55
	v_and_b32_e32 v63, 0xffff0000, v63
	v_fmac_f32_e32 v62, v64, v64
	v_fmac_f32_e32 v62, v63, v63
	v_add_f32_e32 v54, v54, v62
	v_and_b32_e32 v57, 64, v218
	v_xor_b32_e32 v56, 16, v218
	v_add_u32_e32 v57, 64, v57
	v_cmp_lt_i32_e32 vcc, v56, v57
	s_waitcnt vmcnt(0)
	v_pk_add_f32 v[58:59], v[68:69], v[58:59]
	s_nop 0
	v_cvt_pk_bf16_f32 v62, v58, v59
	v_pk_add_f32 v[60:61], v[70:71], v[60:61]
	v_and_b32_e32 v64, 0xffff0000, v62
	v_lshlrev_b32_e32 v55, 16, v62
	v_mul_f32_e32 v64, v64, v64
	v_cvt_pk_bf16_f32 v63, v60, v61
	v_fmac_f32_e32 v64, v55, v55
	v_lshlrev_b32_e32 v65, 16, v63
	v_and_b32_e32 v66, 0xffff0000, v63
	v_fmac_f32_e32 v64, v65, v65
	v_cndmask_b32_e32 v56, v218, v56, vcc
	v_fmac_f32_e32 v64, v66, v66
	v_lshlrev_b32_e32 v56, 2, v56
	v_add_f32_e32 v54, v54, v64
	ds_bpermute_b32 v55, v56, v54
	v_xor_b32_e32 v64, 32, v218
	v_cmp_lt_i32_e32 vcc, v64, v57
	global_store_dwordx4 v[76:77], v[58:61], off offset:192
	global_store_dwordx2 v[78:79], v[62:63], off offset:96
	v_cndmask_b32_e32 v57, v218, v64, vcc
	s_waitcnt lgkmcnt(0)
	v_add_f32_e32 v54, v54, v55
	v_lshlrev_b32_e32 v57, 2, v57
	ds_bpermute_b32 v55, v57, v54
	v_cmp_eq_u32_e32 vcc, 0, v80
	s_and_saveexec_b64 s[28:29], vcc
	s_cbranch_execz .LBB0_98
	v_lshl_add_u64 v[58:59], v[0:1], 2, s[24:25]
	s_waitcnt lgkmcnt(0)
	v_add_f32_e32 v1, v54, v55
	global_atomic_add_f32 v[58:59], v1, off

; __device__ __forceinline__ void gemm_mainloop_d(const bf16_t* __restrict__ Ap, int lda, const bf16_t* __restrict__ Bt, int K,
;                                                 int m0, int n0, f32x4 (&acc)[4][4], char* lds) {
;     ...
;   auto dma = [&](int kt, int st) {
;     char* la = lds + st * 32768; char* lb = la + 16384;
; #pragma unroll
;     for (int i = 0; i < 4; i++) {
;       const int row = i * 32 + lrow; const int c = cph ^ ((row >> 1) & 7);
;       __builtin_amdgcn_global_load_lds((const unsigned*)(Ap + (size_t)(m0 + row) * lda + kt * 64 + c * 8), (__attribute__((address_space(3))) unsigned*)(la + i * 4096 + tid * 16), 16, 0, 0);
;       __builtin_amdgcn_global_load_lds((const unsigned*)(Bt + (size_t)(n0 + row) * K + kt * 64 + c * 8), (__attribute__((address_space(3))) unsigned*)(lb + i * 4096 + tid * 16), 16, 0, 0);
;     }
;   };
;   dma(0, 0);
;   asm volatile("s_waitcnt vmcnt(0)" ::: "memory"); __builtin_amdgcn_s_barrier(); asm volatile("" ::: "memory");
;   for (int kt = 0; kt < nk; kt++) {
;     const int st = kt & 1;
;     if (kt + 1 < nk) dma(kt + 1, st ^ 1);
;     const char* la = lds + st * 32768; const char* lb = la + 16384;
;     bf16x8 af[2][4], bfv[2][4];
; #pragma unroll
;     for (int kc = 0; kc < 2; kc++) {
; #pragma unroll
;       for (int m = 0; m < 4; m++) { const int row = wr * 64 + m * 16 + fr; af[kc][m] = *(const bf16x8*)(la + (row * 8 + ((kc * 4 + fq) ^ ((row >> 1) & 7))) * 16); }
; #pragma unroll
;       for (int n = 0; n < 4; n++) { const int row = wc * 64 + n * 16 + fr; bfv[kc][n] = *(const bf16x8*)(lb + (row * 8 + ((kc * 4 + fq) ^ ((row >> 1) & 7))) * 16); }
;     }
;     __builtin_amdgcn_s_setprio(1);
; #pragma unroll
;     for (int kc = 0; kc < 2; kc++)
; #pragma unroll
;       for (int m = 0; m < 4; m++)
; #pragma unroll
;         for (int n = 0; n < 4; n++) acc[m][n] = __builtin_amdgcn_mfma_f32_16x16x32_bf16(bfv[kc][n], af[kc][m], acc[m][n], 0, 0, 0);
;     __builtin_amdgcn_s_setprio(0);
;     asm volatile("s_waitcnt vmcnt(0) lgkmcnt(0)" ::: "memory"); __builtin_amdgcn_s_barrier(); asm volatile("" ::: "memory");
;   }
.LBB0_109:
	s_setprio 3
	s_and_b32 s34, s25, 0x8000
	s_xor_b32 s35, s34, 0x8000
	s_add_i32 s35, s35, vcc_hi
	s_mov_b32 m0, s35
	s_add_i32 vcc_lo, s35, 0x4000
	global_load_lds_dwordx4 v150, s[46:47]
	s_mov_b32 m0, vcc_lo
	s_add_i32 vcc_lo, s35, 0x1000
	global_load_lds_dwordx4 v151, s[46:47]
	s_mov_b32 m0, vcc_lo
	s_add_i32 vcc_lo, s35, 0x5000
	global_load_lds_dwordx4 v152, s[46:47]
	s_mov_b32 m0, vcc_lo
	s_add_i32 vcc_lo, s35, 0x2000
	global_load_lds_dwordx4 v153, s[46:47]
	s_mov_b32 m0, vcc_lo
	s_add_i32 vcc_lo, s35, 0x6000
	global_load_lds_dwordx4 v154, s[46:47]
	s_mov_b32 m0, vcc_lo
	s_add_i32 vcc_lo, s35, 0x3000
	global_load_lds_dwordx4 v155, s[46:47]
	s_mov_b32 m0, vcc_lo
	s_add_i32 vcc_lo, s35, 0x7000
	global_load_lds_dwordx4 v156, s[46:47]
	s_mov_b32 m0, vcc_lo
	s_nop 0
	global_load_lds_dwordx4 v157, s[46:47]
	v_add_u32_e32 v150, 0x80, v150
	v_add_u32_e32 v151, 0x80, v151
	v_add_u32_e32 v152, 0x80, v152
	v_add_u32_e32 v153, 0x80, v153
	v_add_u32_e32 v154, 0x80, v154
	v_add_u32_e32 v155, 0x80, v155
	v_add_u32_e32 v156, 0x80, v156
	v_add_u32_e32 v157, 0x80, v157
	v_add_u32_e32 v98, s34, v85
	v_add_u32_e32 v114, s34, v84
	v_add_u32_e32 v130, s34, v83
	v_add_u32_e32 v146, s34, v2
	ds_read_b128 v[86:89], v98
	ds_read_b128 v[90:93], v98 offset:2048
	ds_read_b128 v[94:97], v98 offset:4096
	ds_read_b128 v[98:101], v98 offset:6144
	ds_read_b128 v[102:105], v114 offset:16384
	ds_read_b128 v[106:109], v114 offset:18432
	ds_read_b128 v[110:113], v114 offset:20480
	ds_read_b128 v[114:117], v114 offset:22528
	ds_read_b128 v[118:121], v130
	ds_read_b128 v[122:125], v130 offset:2048
	ds_read_b128 v[126:129], v130 offset:4096
	ds_read_b128 v[130:133], v130 offset:6144
	ds_read_b128 v[134:137], v146 offset:16384
	ds_read_b128 v[138:141], v146 offset:18432
	ds_read_b128 v[142:145], v146 offset:20480
	ds_read_b128 v[146:149], v146 offset:22528
	s_setprio 1
	s_waitcnt lgkmcnt(0)
	v_mfma_f32_16x16x32_bf16 v[64:67], v[102:105], v[86:89], v[64:67]
	v_mfma_f32_16x16x32_bf16 v[60:63], v[106:109], v[86:89], v[60:63]
	v_mfma_f32_16x16x32_bf16 v[56:59], v[110:113], v[86:89], v[56:59]
	v_mfma_f32_16x16x32_bf16 v[52:55], v[114:117], v[86:89], v[52:55]
	v_mfma_f32_16x16x32_bf16 v[48:51], v[102:105], v[90:93], v[48:51]
	v_mfma_f32_16x16x32_bf16 v[44:47], v[106:109], v[90:93], v[44:47]
	v_mfma_f32_16x16x32_bf16 v[40:43], v[110:113], v[90:93], v[40:43]
	v_mfma_f32_16x16x32_bf16 v[36:39], v[114:117], v[90:93], v[36:39]
	v_mfma_f32_16x16x32_bf16 v[32:35], v[102:105], v[94:97], v[32:35]
	v_mfma_f32_16x16x32_bf16 v[28:31], v[106:109], v[94:97], v[28:31]
	v_mfma_f32_16x16x32_bf16 v[24:27], v[110:113], v[94:97], v[24:27]
	v_mfma_f32_16x16x32_bf16 v[20:23], v[114:117], v[94:97], v[20:23]
	v_mfma_f32_16x16x32_bf16 v[16:19], v[102:105], v[98:101], v[16:19]
	v_mfma_f32_16x16x32_bf16 v[12:15], v[106:109], v[98:101], v[12:15]
	v_mfma_f32_16x16x32_bf16 v[8:11], v[110:113], v[98:101], v[8:11]
	v_mfma_f32_16x16x32_bf16 v[4:7], v[114:117], v[98:101], v[4:7]
	v_mfma_f32_16x16x32_bf16 v[64:67], v[134:137], v[118:121], v[64:67]
	v_mfma_f32_16x16x32_bf16 v[60:63], v[138:141], v[118:121], v[60:63]
	v_mfma_f32_16x16x32_bf16 v[56:59], v[142:145], v[118:121], v[56:59]
	v_mfma_f32_16x16x32_bf16 v[52:55], v[146:149], v[118:121], v[52:55]
	v_mfma_f32_16x16x32_bf16 v[48:51], v[134:137], v[122:125], v[48:51]
	v_mfma_f32_16x16x32_bf16 v[44:47], v[138:141], v[122:125], v[44:47]
	v_mfma_f32_16x16x32_bf16 v[40:43], v[142:145], v[122:125], v[40:43]
	v_mfma_f32_16x16x32_bf16 v[36:39], v[146:149], v[122:125], v[36:39]
	v_mfma_f32_16x16x32_bf16 v[32:35], v[134:137], v[126:129], v[32:35]
	v_mfma_f32_16x16x32_bf16 v[28:31], v[138:141], v[126:129], v[28:31]
	v_mfma_f32_16x16x32_bf16 v[24:27], v[142:145], v[126:129], v[24:27]
	v_mfma_f32_16x16x32_bf16 v[20:23], v[146:149], v[126:129], v[20:23]
	v_mfma_f32_16x16x32_bf16 v[16:19], v[134:137], v[130:133], v[16:19]
	v_mfma_f32_16x16x32_bf16 v[12:15], v[138:141], v[130:133], v[12:15]
	v_mfma_f32_16x16x32_bf16 v[8:11], v[142:145], v[130:133], v[8:11]
	v_mfma_f32_16x16x32_bf16 v[4:7], v[146:149], v[130:133], v[4:7]
	s_setprio 0
	s_waitcnt vmcnt(0) lgkmcnt(0)
	s_barrier
	s_add_u32 s26, s26, 0x80
	s_addc_u32 s27, s27, 0
	s_add_i32 s25, s25, 0x8000
	s_cmpk_lg_i32 s26, 0x780
	s_cbranch_scc1 .LBB0_109
; __device__ __forceinline__ unsigned char* WS(const Params& p) { unsigned z = 0; asm volatile("" : "+s"(z)); return p.ws + z; }
; __device__ __forceinline__ void gemm_mainloop_d(const bf16_t* __restrict__ Ap, int lda, const bf16_t* __restrict__ Bt, int K,
;                                                 int m0, int n0, f32x4 (&acc)[4][4], char* lds) {
;     ...
;     const char* la = lds + st * 32768; const char* lb = la + 16384;
;     bf16x8 af[2][4], bfv[2][4];
; #pragma unroll
;     for (int kc = 0; kc < 2; kc++) {
; #pragma unroll
;       for (int m = 0; m < 4; m++) { const int row = wr * 64 + m * 16 + fr; af[kc][m] = *(const bf16x8*)(la + (row * 8 + ((kc * 4 + fq) ^ ((row >> 1) & 7))) * 16); }
; #pragma unroll
;       for (int n = 0; n < 4; n++) { const int row = wc * 64 + n * 16 + fr; bfv[kc][n] = *(const bf16x8*)(lb + (row * 8 + ((kc * 4 + fq) ^ ((row >> 1) & 7))) * 16); }
;     }
;     __builtin_amdgcn_s_setprio(1);
; #pragma unroll
;     for (int kc = 0; kc < 2; kc++)
; #pragma unroll
;       for (int m = 0; m < 4; m++)
; #pragma unroll
;         for (int n = 0; n < 4; n++) acc[m][n] = __builtin_amdgcn_mfma_f32_16x16x32_bf16(bfv[kc][n], af[kc][m], acc[m][n], 0, 0, 0);
;     __builtin_amdgcn_s_setprio(0);
;     asm volatile("s_waitcnt vmcnt(0) lgkmcnt(0)" ::: "memory"); __builtin_amdgcn_s_barrier(); asm volatile("" ::: "memory");
;   }
; __device__ __forceinline__ void gemm_GU(const Params& p, int item, char* lds) {
;     ...
;   const float* rssg = (const float*)(WS(p) + OFF_RSS) + T + m0;
;   bf16_t* U = (bf16_t*)(WS(p) + OFF_U);
; #pragma unroll
;   for (int m = 0; m < 4; m++) {
;     const int rl = wr * 64 + m * 16 + fr; const float r = rsqrtf(rssg[rl] * (1.f / 1024.f) + 1e-6f);
	v_add_u32_e32 v0, 0, v85
	ds_read_b128 v[68:71], v0 offset:32768
	ds_read_b128 v[72:75], v0 offset:34816
	ds_read_b128 v[76:79], v0 offset:36864
	ds_read_b128 v[86:89], v0 offset:38912
	v_add_u32_e32 v0, 0, v84
	ds_read_b128 v[90:93], v0 offset:49152
	ds_read_b128 v[94:97], v0 offset:51200
	ds_read_b128 v[98:101], v0 offset:53248
	ds_read_b128 v[102:105], v0 offset:55296
	v_add_u32_e32 v0, 0, v83
	ds_read_b128 v[80:83], v0 offset:32768
	ds_read_b128 v[106:109], v0 offset:34816
	ds_read_b128 v[110:113], v0 offset:36864
	ds_read_b128 v[114:117], v0 offset:38912
	v_add_u32_e32 v0, 0, v2
	ds_read_b128 v[118:121], v0 offset:49152
	ds_read_b128 v[122:125], v0 offset:51200
	ds_read_b128 v[126:129], v0 offset:53248
	ds_read_b128 v[130:133], v0 offset:55296
	s_setprio 1
	s_waitcnt lgkmcnt(0)
	v_mfma_f32_16x16x32_bf16 v[64:67], v[90:93], v[68:71], v[64:67]
	v_mfma_f32_16x16x32_bf16 v[60:63], v[94:97], v[68:71], v[60:63]
	v_mfma_f32_16x16x32_bf16 v[56:59], v[98:101], v[68:71], v[56:59]
	v_mfma_f32_16x16x32_bf16 v[52:55], v[102:105], v[68:71], v[52:55]
	v_mfma_f32_16x16x32_bf16 v[48:51], v[90:93], v[72:75], v[48:51]
	v_mfma_f32_16x16x32_bf16 v[44:47], v[94:97], v[72:75], v[44:47]
	v_mfma_f32_16x16x32_bf16 v[68:71], v[98:101], v[72:75], v[40:43]
	v_mfma_f32_16x16x32_bf16 v[72:75], v[102:105], v[72:75], v[36:39]
	v_mfma_f32_16x16x32_bf16 v[32:35], v[90:93], v[76:79], v[32:35]
	v_mfma_f32_16x16x32_bf16 v[28:31], v[94:97], v[76:79], v[28:31]
	v_mfma_f32_16x16x32_bf16 v[134:137], v[98:101], v[76:79], v[24:27]
	v_mfma_f32_16x16x32_bf16 v[76:79], v[102:105], v[76:79], v[20:23]
	v_mfma_f32_16x16x32_bf16 v[16:19], v[90:93], v[86:89], v[16:19]
	v_mfma_f32_16x16x32_bf16 v[12:15], v[94:97], v[86:89], v[12:15]
	v_mfma_f32_16x16x32_bf16 v[90:93], v[98:101], v[86:89], v[8:11]
	v_mfma_f32_16x16x32_bf16 v[84:87], v[102:105], v[86:89], v[4:7]
	v_mfma_f32_16x16x32_bf16 v[64:67], v[118:121], v[80:83], v[64:67]
	v_mfma_f32_16x16x32_bf16 v[60:63], v[122:125], v[80:83], v[60:63]
	v_mfma_f32_16x16x32_bf16 v[56:59], v[126:129], v[80:83], v[56:59]
	v_mfma_f32_16x16x32_bf16 v[52:55], v[130:133], v[80:83], v[52:55]
	v_mfma_f32_16x16x32_bf16 v[40:43], v[118:121], v[106:109], v[48:51]
	v_mfma_f32_16x16x32_bf16 v[48:51], v[122:125], v[106:109], v[44:47]
	v_mfma_f32_16x16x32_bf16 v[36:39], v[126:129], v[106:109], v[68:71]
	v_mfma_f32_16x16x32_bf16 v[44:47], v[130:133], v[106:109], v[72:75]
	v_mfma_f32_16x16x32_bf16 v[24:27], v[118:121], v[110:113], v[32:35]
	v_mfma_f32_16x16x32_bf16 v[32:35], v[122:125], v[110:113], v[28:31]
	v_mfma_f32_16x16x32_bf16 v[20:23], v[126:129], v[110:113], v[134:137]
	v_mfma_f32_16x16x32_bf16 v[28:31], v[130:133], v[110:113], v[76:79]
	v_mfma_f32_16x16x32_bf16 v[8:11], v[118:121], v[114:117], v[16:19]
	v_mfma_f32_16x16x32_bf16 v[16:19], v[122:125], v[114:117], v[12:15]
	v_mfma_f32_16x16x32_bf16 v[4:7], v[126:129], v[114:117], v[90:93]
	v_mfma_f32_16x16x32_bf16 v[12:15], v[130:133], v[114:117], v[84:87]
	s_setprio 0
	v_mov_b32_e32 v2, v198
	s_mov_b32 s25, s89
	s_waitcnt vmcnt(0) lgkmcnt(0)
	s_barrier
	s_add_u32 s34, s46, s25
	s_addc_u32 s35, s47, 0
	s_ashr_i32 s25, s24, 31
	v_and_b32_e32 v0, 15, v2
	s_lshl_b64 s[26:27], s[24:25], 2
	v_ashrrev_i32_e32 v1, 1, v2
	s_movk_i32 s4, 0xffc0
	s_add_u32 s26, s34, s26
	v_and_or_b32 v0, v1, s4, v0
	s_addc_u32 s27, s35, s27
	v_ashrrev_i32_e32 v1, 31, v0
	v_lshl_add_u64 v[68:69], v[0:1], 2, s[26:27]
	s_mov_b32 s26, 0xff9c000
	v_add_co_u32_e32 v70, vcc, s26, v68
	s_mov_b32 s25, s89
	s_nop 0
	v_addc_co_u32_e32 v71, vcc, 0, v69, vcc
	global_load_dword v74, v[70:71], off
	v_mov_b32_e32 v71, v64
	v_mov_b32_e32 v64, v61
	v_mov_b32_e32 v61, v66
	v_mov_b32_e32 v66, v63
	v_mov_b32_e32 v63, v56
	v_mov_b32_e32 v56, v53
	v_mov_b32_e32 v70, v60
	v_mov_b32_e32 v60, v62
	v_mov_b32_e32 v62, v52
	v_mov_b32_e32 v72, v54
	v_mov_b32_e32 v73, v58
	v_mov_b32_e32 v58, v55
	v_lshrrev_b32_e32 v1, 1, v2
	v_lshrrev_b32_e32 v2, 2, v2
	s_add_u32 s26, s46, s25
	v_and_b32_e32 v52, 12, v2
	v_add_u32_e32 v2, s24, v0
	s_addc_u32 s27, s47, 0
	s_mov_b64 s[24:25], 0xff9c000
	v_lshl_add_u64 v[54:55], v[68:69], 0, s[24:25]
	s_add_u32 s24, s26, 0x768000
	v_and_b32_e32 v1, 32, v1
	s_addc_u32 s25, s27, 0
	s_ashr_i32 s26, s31, 1
	v_or3_b32 v52, v1, s26, v52
	v_mov_b64_e32 v[0:1], s[24:25]
	v_mad_i64_i32 v[68:69], s[24:25], v2, s33, v[0:1]
	s_add_i32 s30, s30, s77
	s_add_i32 s29, s29, s2
	s_add_i32 s28, s28, s3
	s_cmpk_gt_i32 s30, 0x15ff
	s_waitcnt vmcnt(0)
; __device__ __forceinline__ unsigned pk2(float lo, float hi) { unsigned r; asm("v_cvt_pk_bf16_f32 %0, %1, %2" : "=v"(r) : "v"(lo), "v"(hi)); return r; }
; __device__ __forceinline__ float sigmoidf_(float x) { return __builtin_amdgcn_rcpf(1.0f + __expf(-x)); }
; __device__ __forceinline__ void gemm_GU(const Params& p, int item, char* lds) {
;     ...
;   for (int m = 0; m < 4; m++) {
;     const int rl = wr * 64 + m * 16 + fr; const float r = rsqrtf(rssg[rl] * (1.f / 1024.f) + 1e-6f);
; #pragma unroll
;     for (int i = 0; i < 2; i++) {
;       f32x4 g = acc[m][2 * i] * r, u = acc[m][2 * i + 1] * r, o;
; #pragma unroll
;       for (int j = 0; j < 4; j++) o[j] = g[j] * sigmoidf_(g[j]) * u[j];
;       const int col = (n0 >> 1) + wc * 32 + i * 16 + fq * 4;
;       u32x2 w; w[0] = pk2(o[0], o[1]); w[1] = pk2(o[2], o[3]);
;       *(u32x2*)(U + (size_t)(m0 + rl) * DFF + col) = w;
;     }
;   }
	v_fmamk_f32 v53, v74, 0x3a800000, v200
	v_mul_f32_e32 v74, 0x4b800000, v53
	v_cmp_gt_f32_e32 vcc, s83, v53
	s_nop 1
	v_cndmask_b32_e32 v53, v53, v74, vcc
	v_rsq_f32_e32 v74, v53
	v_ashrrev_i32_e32 v53, 31, v52
	v_lshlrev_b64 v[52:53], 1, v[52:53]
	v_lshl_add_u64 v[68:69], v[68:69], 0, v[52:53]
	v_mul_f32_e32 v75, 0x45800000, v74
	v_cndmask_b32_e32 v74, v74, v75, vcc
	v_pk_mul_f32 v[60:61], v[60:61], v[74:75] op_sel_hi:[1,0]
	v_pk_mul_f32 v[70:71], v[70:71], v[74:75] op_sel_hi:[1,0]
	v_pk_mul_f32 v[64:65], v[64:65], v[74:75] op_sel_hi:[1,0]
	v_pk_mul_f32 v[66:67], v[66:67], v[74:75] op_sel_hi:[1,0]
	v_mul_f32_e32 v76, 0xbfb8aa3b, v61
	v_pk_mul_f32 v[62:63], v[62:63], v[74:75] op_sel_hi:[1,0]
	v_pk_mul_f32 v[56:57], v[56:57], v[74:75] op_sel_hi:[1,0]
	v_pk_mul_f32 v[72:73], v[72:73], v[74:75] op_sel_hi:[1,0]
	v_pk_mul_f32 v[58:59], v[58:59], v[74:75] op_sel_hi:[1,0]
	v_mul_f32_e32 v74, 0xbfb8aa3b, v71
	v_mul_f32_e32 v75, 0xbfb8aa3b, v65
	v_mul_f32_e32 v77, 0xbfb8aa3b, v67
	v_exp_f32_e32 v76, v76
	v_exp_f32_e32 v74, v74
	v_exp_f32_e32 v75, v75
	v_exp_f32_e32 v77, v77
	v_add_f32_e32 v76, 1.0, v76
	v_mul_f32_e32 v79, 0xbfb8aa3b, v57
	v_add_f32_e32 v74, 1.0, v74
	v_add_f32_e32 v75, 1.0, v75
	v_add_f32_e32 v77, 1.0, v77
	v_rcp_f32_e32 v76, v76
	v_mul_f32_e32 v80, 0xbfb8aa3b, v73
	v_exp_f32_e32 v79, v79
	v_rcp_f32_e32 v74, v74
	v_rcp_f32_e32 v75, v75
	v_rcp_f32_e32 v77, v77
	v_mul_f32_e32 v78, 0xbfb8aa3b, v63
	v_mul_f32_e32 v81, 0xbfb8aa3b, v59
	v_exp_f32_e32 v80, v80
	v_exp_f32_e32 v78, v78
	v_exp_f32_e32 v81, v81
	v_mul_f32_e32 v61, v61, v76
	v_add_f32_e32 v79, 1.0, v79
	v_mul_f32_e32 v71, v71, v74
	v_mul_f32_e32 v65, v65, v75
	v_mul_f32_e32 v67, v67, v77
	v_mul_f32_e32 v61, v60, v61
	v_add_f32_e32 v80, 1.0, v80
	v_rcp_f32_e32 v79, v79
	v_mul_f32_e32 v70, v70, v71
	v_mul_f32_e32 v64, v64, v65
	v_mul_f32_e32 v65, v66, v67
	v_cvt_pk_bf16_f32 v60, v70, v64
	v_cvt_pk_bf16_f32 v61, v61, v65
	v_add_f32_e32 v78, 1.0, v78
	global_store_dwordx2 v[68:69], v[60:61], off
	v_rcp_f32_e32 v60, v80
	v_add_f32_e32 v61, 1.0, v81
	v_rcp_f32_e32 v78, v78
	v_rcp_f32_e32 v61, v61
	v_mul_f32_e32 v57, v57, v79
	v_mul_f32_e32 v56, v56, v57
	v_mul_f32_e32 v57, v73, v60
	v_mul_f32_e32 v63, v63, v78
	v_mul_f32_e32 v57, v72, v57
	v_mul_f32_e32 v59, v59, v61
	v_mul_f32_e32 v62, v62, v63
	v_mul_f32_e32 v58, v58, v59
	v_cvt_pk_bf16_f32 v56, v62, v56
	v_cvt_pk_bf16_f32 v57, v57, v58
	global_store_dwordx2 v[68:69], v[56:57], off offset:32
	global_load_dword v58, v[54:55], off offset:64
	v_mov_b32_e32 v57, v40
	v_mov_b32_e32 v40, v49
	v_mov_b32_e32 v49, v42
	v_mov_b32_e32 v42, v51
	v_mov_b32_e32 v51, v36
	v_mov_b32_e32 v36, v45
	v_mov_b32_e32 v45, v38
	v_mov_b32_e32 v38, v47
	v_mov_b32_e32 v56, v48
	v_mov_b32_e32 v48, v50
	v_mov_b32_e32 v50, v44
	v_mov_b32_e32 v44, v46
	v_add_u32_e32 v46, 16, v2
	s_waitcnt vmcnt(0)
	v_fmamk_f32 v47, v58, 0x3a800000, v200
	v_mul_f32_e32 v58, 0x4b800000, v47
	v_cmp_gt_f32_e32 vcc, s83, v47
	s_nop 1
	v_cndmask_b32_e32 v47, v47, v58, vcc
	v_rsq_f32_e32 v58, v47
	v_mad_i64_i32 v[46:47], s[24:25], v46, s33, v[0:1]
	v_lshl_add_u64 v[46:47], v[46:47], 0, v[52:53]
	v_mul_f32_e32 v59, 0x45800000, v58
	v_cndmask_b32_e32 v58, v58, v59, vcc
	v_pk_mul_f32 v[56:57], v[56:57], v[58:59] op_sel_hi:[1,0]
	v_pk_mul_f32 v[40:41], v[40:41], v[58:59] op_sel_hi:[1,0]
	v_pk_mul_f32 v[48:49], v[48:49], v[58:59] op_sel_hi:[1,0]
	v_pk_mul_f32 v[42:43], v[42:43], v[58:59] op_sel_hi:[1,0]
	v_pk_mul_f32 v[36:37], v[36:37], v[58:59] op_sel_hi:[1,0]
	v_pk_mul_f32 v[38:39], v[38:39], v[58:59] op_sel_hi:[1,0]
	v_pk_mul_f32 v[50:51], v[50:51], v[58:59] op_sel_hi:[1,0]
	v_pk_mul_f32 v[44:45], v[44:45], v[58:59] op_sel_hi:[1,0]
	v_mul_f32_e32 v58, 0xbfb8aa3b, v57
	v_mul_f32_e32 v59, 0xbfb8aa3b, v41
	v_mul_f32_e32 v60, 0xbfb8aa3b, v49
	v_mul_f32_e32 v61, 0xbfb8aa3b, v43
	v_mul_f32_e32 v63, 0xbfb8aa3b, v37
	v_mul_f32_e32 v65, 0xbfb8aa3b, v39
	v_mul_f32_e32 v62, 0xbfb8aa3b, v51
	v_mul_f32_e32 v64, 0xbfb8aa3b, v45
	v_exp_f32_e32 v58, v58
	v_exp_f32_e32 v59, v59
	v_exp_f32_e32 v60, v60
	v_exp_f32_e32 v61, v61
	v_exp_f32_e32 v63, v63
	v_exp_f32_e32 v65, v65
	v_exp_f32_e32 v62, v62
	v_exp_f32_e32 v64, v64
	v_add_f32_e32 v58, 1.0, v58
	v_add_f32_e32 v59, 1.0, v59
	v_add_f32_e32 v60, 1.0, v60
	v_add_f32_e32 v61, 1.0, v61
	v_add_f32_e32 v63, 1.0, v63
	v_add_f32_e32 v65, 1.0, v65
	v_add_f32_e32 v62, 1.0, v62
	v_add_f32_e32 v64, 1.0, v64
	v_rcp_f32_e32 v58, v58
	v_rcp_f32_e32 v59, v59
	v_rcp_f32_e32 v60, v60
	v_rcp_f32_e32 v61, v61
	v_rcp_f32_e32 v63, v63
	v_rcp_f32_e32 v65, v65
	v_rcp_f32_e32 v62, v62
	v_rcp_f32_e32 v64, v64
	v_mul_f32_e32 v57, v57, v58
	v_mul_f32_e32 v41, v41, v59
	v_mul_f32_e32 v49, v49, v60
	v_mul_f32_e32 v43, v43, v61
	v_mul_f32_e32 v37, v37, v63
	v_mul_f32_e32 v39, v39, v65
	v_mul_f32_e32 v51, v51, v62
	v_mul_f32_e32 v45, v45, v64
	v_mul_f32_e32 v56, v56, v57
	v_mul_f32_e32 v40, v40, v41
	v_mul_f32_e32 v41, v48, v49
	v_mul_f32_e32 v42, v42, v43
	v_mul_f32_e32 v48, v36, v37
	v_mul_f32_e32 v39, v38, v39
	v_cvt_pk_bf16_f32 v36, v56, v40
	v_cvt_pk_bf16_f32 v37, v41, v42
	v_mul_f32_e32 v43, v50, v51
	v_mul_f32_e32 v44, v44, v45
	v_cvt_pk_bf16_f32 v38, v43, v48
	v_cvt_pk_bf16_f32 v39, v44, v39
	global_store_dwordx2 v[46:47], v[36:37], off
	global_store_dwordx2 v[46:47], v[38:39], off offset:32
	global_load_dword v38, v[54:55], off offset:128
	v_mov_b32_e32 v37, v24
	v_mov_b32_e32 v24, v33
	v_mov_b32_e32 v33, v26
	v_mov_b32_e32 v26, v35
	v_mov_b32_e32 v35, v20
	v_mov_b32_e32 v20, v29
	v_mov_b32_e32 v29, v22
	v_mov_b32_e32 v22, v31
	v_mov_b32_e32 v36, v32
	v_mov_b32_e32 v32, v34
	v_mov_b32_e32 v34, v28
	v_mov_b32_e32 v28, v30
	v_add_u32_e32 v30, 32, v2
	v_add_u32_e32 v2, 48, v2
	s_waitcnt vmcnt(0)
; __device__ __forceinline__ unsigned pk2(float lo, float hi) { unsigned r; asm("v_cvt_pk_bf16_f32 %0, %1, %2" : "=v"(r) : "v"(lo), "v"(hi)); return r; }
; __device__ __forceinline__ float sigmoidf_(float x) { return __builtin_amdgcn_rcpf(1.0f + __expf(-x)); }
; __device__ __forceinline__ void gemm_GU(const Params& p, int item, char* lds) {
;     ...
;   for (int m = 0; m < 4; m++) {
;     const int rl = wr * 64 + m * 16 + fr; const float r = rsqrtf(rssg[rl] * (1.f / 1024.f) + 1e-6f);
; #pragma unroll
;     for (int i = 0; i < 2; i++) {
;       f32x4 g = acc[m][2 * i] * r, u = acc[m][2 * i + 1] * r, o;
; #pragma unroll
;       for (int j = 0; j < 4; j++) o[j] = g[j] * sigmoidf_(g[j]) * u[j];
;       const int col = (n0 >> 1) + wc * 32 + i * 16 + fq * 4;
;       u32x2 w; w[0] = pk2(o[0], o[1]); w[1] = pk2(o[2], o[3]);
;       *(u32x2*)(U + (size_t)(m0 + rl) * DFF + col) = w;
;     }
;   }
;   __syncthreads();
	v_fmamk_f32 v31, v38, 0x3a800000, v200
	v_mul_f32_e32 v38, 0x4b800000, v31
	v_cmp_gt_f32_e32 vcc, s83, v31
	s_nop 1
	v_cndmask_b32_e32 v31, v31, v38, vcc
	v_rsq_f32_e32 v38, v31
	v_mad_i64_i32 v[30:31], s[24:25], v30, s33, v[0:1]
	v_lshl_add_u64 v[30:31], v[30:31], 0, v[52:53]
	v_mul_f32_e32 v39, 0x45800000, v38
	v_cndmask_b32_e32 v38, v38, v39, vcc
	v_pk_mul_f32 v[36:37], v[36:37], v[38:39] op_sel_hi:[1,0]
	v_pk_mul_f32 v[24:25], v[24:25], v[38:39] op_sel_hi:[1,0]
	v_pk_mul_f32 v[32:33], v[32:33], v[38:39] op_sel_hi:[1,0]
	v_pk_mul_f32 v[26:27], v[26:27], v[38:39] op_sel_hi:[1,0]
	v_pk_mul_f32 v[20:21], v[20:21], v[38:39] op_sel_hi:[1,0]
	v_pk_mul_f32 v[22:23], v[22:23], v[38:39] op_sel_hi:[1,0]
	v_pk_mul_f32 v[34:35], v[34:35], v[38:39] op_sel_hi:[1,0]
	v_pk_mul_f32 v[28:29], v[28:29], v[38:39] op_sel_hi:[1,0]
	v_mul_f32_e32 v38, 0xbfb8aa3b, v37
	v_mul_f32_e32 v39, 0xbfb8aa3b, v25
	v_mul_f32_e32 v40, 0xbfb8aa3b, v33
	v_mul_f32_e32 v41, 0xbfb8aa3b, v27
	v_mul_f32_e32 v43, 0xbfb8aa3b, v21
	v_mul_f32_e32 v45, 0xbfb8aa3b, v23
	v_mul_f32_e32 v42, 0xbfb8aa3b, v35
	v_mul_f32_e32 v44, 0xbfb8aa3b, v29
	v_exp_f32_e32 v38, v38
	v_exp_f32_e32 v39, v39
	v_exp_f32_e32 v40, v40
	v_exp_f32_e32 v41, v41
	v_exp_f32_e32 v43, v43
	v_exp_f32_e32 v45, v45
	v_exp_f32_e32 v42, v42
	v_exp_f32_e32 v44, v44
	v_add_f32_e32 v38, 1.0, v38
	v_add_f32_e32 v39, 1.0, v39
	v_add_f32_e32 v40, 1.0, v40
	v_add_f32_e32 v41, 1.0, v41
	v_add_f32_e32 v43, 1.0, v43
	v_add_f32_e32 v45, 1.0, v45
	v_add_f32_e32 v42, 1.0, v42
	v_add_f32_e32 v44, 1.0, v44
	v_rcp_f32_e32 v38, v38
	v_rcp_f32_e32 v39, v39
	v_rcp_f32_e32 v40, v40
	v_rcp_f32_e32 v41, v41
	v_rcp_f32_e32 v43, v43
	v_rcp_f32_e32 v45, v45
	v_rcp_f32_e32 v42, v42
	v_rcp_f32_e32 v44, v44
	v_mul_f32_e32 v37, v37, v38
	v_mul_f32_e32 v25, v25, v39
	v_mul_f32_e32 v33, v33, v40
	v_mul_f32_e32 v27, v27, v41
	v_mul_f32_e32 v21, v21, v43
	v_mul_f32_e32 v23, v23, v45
	v_mul_f32_e32 v35, v35, v42
	v_mul_f32_e32 v29, v29, v44
	v_mul_f32_e32 v36, v36, v37
	v_mul_f32_e32 v24, v24, v25
	v_mul_f32_e32 v25, v32, v33
	v_mul_f32_e32 v26, v26, v27
	v_mul_f32_e32 v32, v20, v21
	v_mul_f32_e32 v23, v22, v23
	v_cvt_pk_bf16_f32 v20, v36, v24
	v_cvt_pk_bf16_f32 v21, v25, v26
	v_mul_f32_e32 v27, v34, v35
	v_mul_f32_e32 v28, v28, v29
	v_cvt_pk_bf16_f32 v22, v27, v32
	v_cvt_pk_bf16_f32 v23, v28, v23
	global_store_dwordx2 v[30:31], v[20:21], off
	global_store_dwordx2 v[30:31], v[22:23], off offset:32
	global_load_dword v22, v[54:55], off offset:192
	v_mov_b32_e32 v20, v16
	v_mov_b32_e32 v16, v18
	v_mov_b32_e32 v18, v12
	v_mov_b32_e32 v12, v14
	v_mov_b32_e32 v21, v8
	v_mov_b32_e32 v8, v17
	v_mov_b32_e32 v17, v10
	v_mov_b32_e32 v10, v19
	v_mov_b32_e32 v19, v4
	v_mov_b32_e32 v4, v13
	v_mov_b32_e32 v13, v6
	v_mov_b32_e32 v6, v15
	v_mad_i64_i32 v[0:1], s[24:25], v2, s33, v[0:1]
	v_lshl_add_u64 v[0:1], v[0:1], 0, v[52:53]
	s_waitcnt vmcnt(0)
	v_fmamk_f32 v14, v22, 0x3a800000, v200
	v_mul_f32_e32 v15, 0x4b800000, v14
	v_cmp_gt_f32_e32 vcc, s83, v14
	s_nop 1
	v_cndmask_b32_e32 v14, v14, v15, vcc
	v_rsq_f32_e32 v14, v14
	s_nop 0
	v_mul_f32_e32 v2, 0x45800000, v14
	v_cndmask_b32_e32 v2, v14, v2, vcc
	v_pk_mul_f32 v[14:15], v[20:21], v[2:3] op_sel_hi:[1,0]
	v_pk_mul_f32 v[8:9], v[8:9], v[2:3] op_sel_hi:[1,0]
	v_pk_mul_f32 v[16:17], v[16:17], v[2:3] op_sel_hi:[1,0]
	v_pk_mul_f32 v[10:11], v[10:11], v[2:3] op_sel_hi:[1,0]
	v_pk_mul_f32 v[4:5], v[4:5], v[2:3] op_sel_hi:[1,0]
	v_pk_mul_f32 v[6:7], v[6:7], v[2:3] op_sel_hi:[1,0]
	v_pk_mul_f32 v[18:19], v[18:19], v[2:3] op_sel_hi:[1,0]
	v_pk_mul_f32 v[12:13], v[12:13], v[2:3] op_sel_hi:[1,0]
	v_mul_f32_e32 v2, 0xbfb8aa3b, v15
	v_mul_f32_e32 v20, 0xbfb8aa3b, v9
	v_mul_f32_e32 v21, 0xbfb8aa3b, v17
	v_mul_f32_e32 v22, 0xbfb8aa3b, v11
	v_mul_f32_e32 v24, 0xbfb8aa3b, v5
	v_mul_f32_e32 v26, 0xbfb8aa3b, v7
	v_mul_f32_e32 v23, 0xbfb8aa3b, v19
	v_mul_f32_e32 v25, 0xbfb8aa3b, v13
	v_exp_f32_e32 v2, v2
	v_exp_f32_e32 v20, v20
	v_exp_f32_e32 v21, v21
	v_exp_f32_e32 v22, v22
	v_exp_f32_e32 v24, v24
	v_exp_f32_e32 v26, v26
	v_exp_f32_e32 v23, v23
	v_exp_f32_e32 v25, v25
	v_add_f32_e32 v2, 1.0, v2
	v_add_f32_e32 v20, 1.0, v20
	v_add_f32_e32 v21, 1.0, v21
	v_add_f32_e32 v22, 1.0, v22
	v_add_f32_e32 v24, 1.0, v24
	v_add_f32_e32 v26, 1.0, v26
	v_add_f32_e32 v23, 1.0, v23
	v_add_f32_e32 v25, 1.0, v25
	v_rcp_f32_e32 v2, v2
	v_rcp_f32_e32 v20, v20
	v_rcp_f32_e32 v21, v21
	v_rcp_f32_e32 v22, v22
	v_rcp_f32_e32 v24, v24
	v_rcp_f32_e32 v26, v26
	v_rcp_f32_e32 v23, v23
	v_rcp_f32_e32 v25, v25
	v_mul_f32_e32 v2, v15, v2
	v_mul_f32_e32 v9, v9, v20
	v_mul_f32_e32 v15, v17, v21
	v_mul_f32_e32 v11, v11, v22
	v_mul_f32_e32 v5, v5, v24
	v_mul_f32_e32 v7, v7, v26
	v_mul_f32_e32 v17, v19, v23
	v_mul_f32_e32 v13, v13, v25
	v_mul_f32_e32 v2, v14, v2
	v_mul_f32_e32 v8, v8, v9
	v_mul_f32_e32 v9, v16, v15
	v_mul_f32_e32 v10, v10, v11
	v_mul_f32_e32 v14, v4, v5
	v_mul_f32_e32 v7, v6, v7
	v_cvt_pk_bf16_f32 v4, v2, v8
	v_cvt_pk_bf16_f32 v5, v9, v10
	v_mul_f32_e32 v11, v18, v17
	v_mul_f32_e32 v12, v12, v13
	v_cvt_pk_bf16_f32 v6, v11, v14
	v_cvt_pk_bf16_f32 v7, v12, v7
	global_store_dwordx2 v[0:1], v[4:5], off
	global_store_dwordx2 v[0:1], v[6:7], off offset:32
	s_barrier
	s_cbranch_scc0 .LBB0_108

; __device__ __forceinline__ void gemm_mainloop_d(const bf16_t* __restrict__ Ap, int lda, const bf16_t* __restrict__ Bt, int K,
;                                                 int m0, int n0, f32x4 (&acc)[4][4], char* lds) {
;     ...
;   auto dma = [&](int kt, int st) {
;     char* la = lds + st * 32768; char* lb = la + 16384;
; #pragma unroll
;     for (int i = 0; i < 4; i++) {
;       const int row = i * 32 + lrow; const int c = cph ^ ((row >> 1) & 7);
;       __builtin_amdgcn_global_load_lds((const unsigned*)(Ap + (size_t)(m0 + row) * lda + kt * 64 + c * 8), (__attribute__((address_space(3))) unsigned*)(la + i * 4096 + tid * 16), 16, 0, 0);
;       __builtin_amdgcn_global_load_lds((const unsigned*)(Bt + (size_t)(n0 + row) * K + kt * 64 + c * 8), (__attribute__((address_space(3))) unsigned*)(lb + i * 4096 + tid * 16), 16, 0, 0);
;     }
;   };
;   dma(0, 0);
;   asm volatile("s_waitcnt vmcnt(0)" ::: "memory"); __builtin_amdgcn_s_barrier(); asm volatile("" ::: "memory");
;   for (int kt = 0; kt < nk; kt++) {
;     const int st = kt & 1;
;     if (kt + 1 < nk) dma(kt + 1, st ^ 1);
;     const char* la = lds + st * 32768; const char* lb = la + 16384;
;     bf16x8 af[2][4], bfv[2][4];
; #pragma unroll
;     for (int kc = 0; kc < 2; kc++) {
; #pragma unroll
;       for (int m = 0; m < 4; m++) { const int row = wr * 64 + m * 16 + fr; af[kc][m] = *(const bf16x8*)(la + (row * 8 + ((kc * 4 + fq) ^ ((row >> 1) & 7))) * 16); }
; #pragma unroll
;       for (int n = 0; n < 4; n++) { const int row = wc * 64 + n * 16 + fr; bfv[kc][n] = *(const bf16x8*)(lb + (row * 8 + ((kc * 4 + fq) ^ ((row >> 1) & 7))) * 16); }
;     }
;     __builtin_amdgcn_s_setprio(1);
; #pragma unroll
;     for (int kc = 0; kc < 2; kc++)
; #pragma unroll
;       for (int m = 0; m < 4; m++)
; #pragma unroll
;         for (int n = 0; n < 4; n++) acc[m][n] = __builtin_amdgcn_mfma_f32_16x16x32_bf16(bfv[kc][n], af[kc][m], acc[m][n], 0, 0, 0);
;     __builtin_amdgcn_s_setprio(0);
;     asm volatile("s_waitcnt vmcnt(0) lgkmcnt(0)" ::: "memory"); __builtin_amdgcn_s_barrier(); asm volatile("" ::: "memory");
;   }
.LBB0_126:
	s_setprio 3
	s_and_b32 s37, s34, 0x8000
	s_xor_b32 s43, s37, 0x8000
	s_add_i32 s43, s43, vcc_hi
	s_mov_b32 m0, s43
	s_add_i32 vcc_lo, s43, 0x4000
	global_load_lds_dwordx4 v150, s[46:47]
	s_mov_b32 m0, vcc_lo
	s_add_i32 vcc_lo, s43, 0x1000
	global_load_lds_dwordx4 v151, s[46:47]
	s_mov_b32 m0, vcc_lo
	s_add_i32 vcc_lo, s43, 0x5000
	global_load_lds_dwordx4 v152, s[46:47]
	s_mov_b32 m0, vcc_lo
	s_add_i32 vcc_lo, s43, 0x2000
	global_load_lds_dwordx4 v153, s[46:47]
	s_mov_b32 m0, vcc_lo
	s_add_i32 vcc_lo, s43, 0x6000
	global_load_lds_dwordx4 v154, s[46:47]
	s_mov_b32 m0, vcc_lo
	s_add_i32 vcc_lo, s43, 0x3000
	global_load_lds_dwordx4 v155, s[46:47]
	s_mov_b32 m0, vcc_lo
	s_add_i32 vcc_lo, s43, 0x7000
	global_load_lds_dwordx4 v156, s[46:47]
	s_mov_b32 m0, vcc_lo
	s_nop 0
	global_load_lds_dwordx4 v157, s[46:47]
	v_add_u32_e32 v150, 0x80, v150
	v_add_u32_e32 v151, 0x80, v151
	v_add_u32_e32 v152, 0x80, v152
	v_add_u32_e32 v153, 0x80, v153
	v_add_u32_e32 v154, 0x80, v154
	v_add_u32_e32 v155, 0x80, v155
	v_add_u32_e32 v156, 0x80, v156
	v_add_u32_e32 v157, 0x80, v157
	v_add_u32_e32 v98, s37, v85
	v_add_u32_e32 v114, s37, v84
	v_add_u32_e32 v130, s37, v83
	v_add_u32_e32 v146, s37, v2
	ds_read_b128 v[86:89], v98
	ds_read_b128 v[90:93], v98 offset:2048
	ds_read_b128 v[94:97], v98 offset:4096
	ds_read_b128 v[98:101], v98 offset:6144
	ds_read_b128 v[102:105], v114 offset:16384
	ds_read_b128 v[106:109], v114 offset:18432
	ds_read_b128 v[110:113], v114 offset:20480
	ds_read_b128 v[114:117], v114 offset:22528
	ds_read_b128 v[118:121], v130
	ds_read_b128 v[122:125], v130 offset:2048
	ds_read_b128 v[126:129], v130 offset:4096
	ds_read_b128 v[130:133], v130 offset:6144
	ds_read_b128 v[134:137], v146 offset:16384
	ds_read_b128 v[138:141], v146 offset:18432
	ds_read_b128 v[142:145], v146 offset:20480
	ds_read_b128 v[146:149], v146 offset:22528
	s_setprio 1
	s_waitcnt lgkmcnt(0)
	v_mfma_f32_16x16x32_bf16 v[64:67], v[102:105], v[86:89], v[64:67]
	v_mfma_f32_16x16x32_bf16 v[60:63], v[106:109], v[86:89], v[60:63]
	v_mfma_f32_16x16x32_bf16 v[56:59], v[110:113], v[86:89], v[56:59]
	v_mfma_f32_16x16x32_bf16 v[52:55], v[114:117], v[86:89], v[52:55]
	v_mfma_f32_16x16x32_bf16 v[48:51], v[102:105], v[90:93], v[48:51]
	v_mfma_f32_16x16x32_bf16 v[44:47], v[106:109], v[90:93], v[44:47]
	v_mfma_f32_16x16x32_bf16 v[40:43], v[110:113], v[90:93], v[40:43]
	v_mfma_f32_16x16x32_bf16 v[36:39], v[114:117], v[90:93], v[36:39]
	v_mfma_f32_16x16x32_bf16 v[32:35], v[102:105], v[94:97], v[32:35]
	v_mfma_f32_16x16x32_bf16 v[28:31], v[106:109], v[94:97], v[28:31]
	v_mfma_f32_16x16x32_bf16 v[24:27], v[110:113], v[94:97], v[24:27]
	v_mfma_f32_16x16x32_bf16 v[20:23], v[114:117], v[94:97], v[20:23]
	v_mfma_f32_16x16x32_bf16 v[16:19], v[102:105], v[98:101], v[16:19]
	v_mfma_f32_16x16x32_bf16 v[12:15], v[106:109], v[98:101], v[12:15]
	v_mfma_f32_16x16x32_bf16 v[8:11], v[110:113], v[98:101], v[8:11]
	v_mfma_f32_16x16x32_bf16 v[4:7], v[114:117], v[98:101], v[4:7]
	v_mfma_f32_16x16x32_bf16 v[64:67], v[134:137], v[118:121], v[64:67]
	v_mfma_f32_16x16x32_bf16 v[60:63], v[138:141], v[118:121], v[60:63]
	v_mfma_f32_16x16x32_bf16 v[56:59], v[142:145], v[118:121], v[56:59]
	v_mfma_f32_16x16x32_bf16 v[52:55], v[146:149], v[118:121], v[52:55]
	v_mfma_f32_16x16x32_bf16 v[48:51], v[134:137], v[122:125], v[48:51]
	v_mfma_f32_16x16x32_bf16 v[44:47], v[138:141], v[122:125], v[44:47]
	v_mfma_f32_16x16x32_bf16 v[40:43], v[142:145], v[122:125], v[40:43]
	v_mfma_f32_16x16x32_bf16 v[36:39], v[146:149], v[122:125], v[36:39]
	v_mfma_f32_16x16x32_bf16 v[32:35], v[134:137], v[126:129], v[32:35]
	v_mfma_f32_16x16x32_bf16 v[28:31], v[138:141], v[126:129], v[28:31]
	v_mfma_f32_16x16x32_bf16 v[24:27], v[142:145], v[126:129], v[24:27]
	v_mfma_f32_16x16x32_bf16 v[20:23], v[146:149], v[126:129], v[20:23]
	v_mfma_f32_16x16x32_bf16 v[16:19], v[134:137], v[130:133], v[16:19]
	v_mfma_f32_16x16x32_bf16 v[12:15], v[138:141], v[130:133], v[12:15]
	v_mfma_f32_16x16x32_bf16 v[8:11], v[142:145], v[130:133], v[8:11]
	v_mfma_f32_16x16x32_bf16 v[4:7], v[146:149], v[130:133], v[4:7]
	s_setprio 0
	s_waitcnt vmcnt(0) lgkmcnt(0)
	s_barrier
	s_add_u32 s30, s30, 0x80
	s_addc_u32 s31, s31, 0
	s_add_i32 s34, s34, 0x8000
	s_cmpk_eq_i32 s30, 0x780
	s_cbranch_scc0 .LBB0_126
; __device__ __forceinline__ void gemm_mainloop_d(const bf16_t* __restrict__ Ap, int lda, const bf16_t* __restrict__ Bt, int K,
;                                                 int m0, int n0, f32x4 (&acc)[4][4], char* lds) {
;     ...
;     const char* la = lds + st * 32768; const char* lb = la + 16384;
;     bf16x8 af[2][4], bfv[2][4];
; #pragma unroll
;     for (int kc = 0; kc < 2; kc++) {
; #pragma unroll
;       for (int m = 0; m < 4; m++) { const int row = wr * 64 + m * 16 + fr; af[kc][m] = *(const bf16x8*)(la + (row * 8 + ((kc * 4 + fq) ^ ((row >> 1) & 7))) * 16); }
; #pragma unroll
;       for (int n = 0; n < 4; n++) { const int row = wc * 64 + n * 16 + fr; bfv[kc][n] = *(const bf16x8*)(lb + (row * 8 + ((kc * 4 + fq) ^ ((row >> 1) & 7))) * 16); }
;     }
;     __builtin_amdgcn_s_setprio(1);
; #pragma unroll
;     for (int kc = 0; kc < 2; kc++)
; #pragma unroll
;       for (int m = 0; m < 4; m++)
; #pragma unroll
;         for (int n = 0; n < 4; n++) acc[m][n] = __builtin_amdgcn_mfma_f32_16x16x32_bf16(bfv[kc][n], af[kc][m], acc[m][n], 0, 0, 0);
;     __builtin_amdgcn_s_setprio(0);
;     asm volatile("s_waitcnt vmcnt(0) lgkmcnt(0)" ::: "memory"); __builtin_amdgcn_s_barrier(); asm volatile("" ::: "memory");
;   }
	v_add_u32_e32 v0, 0, v85
	ds_read_b128 v[68:71], v0 offset:32768
	ds_read_b128 v[72:75], v0 offset:34816
	ds_read_b128 v[76:79], v0 offset:36864
	ds_read_b128 v[86:89], v0 offset:38912
	v_add_u32_e32 v0, 0, v84
	ds_read_b128 v[90:93], v0 offset:49152
	ds_read_b128 v[94:97], v0 offset:51200
	ds_read_b128 v[98:101], v0 offset:53248
	ds_read_b128 v[102:105], v0 offset:55296
	v_add_u32_e32 v0, 0, v83
	s_add_u32 s30, s46, s35
	ds_read_b128 v[80:83], v0 offset:32768
	ds_read_b128 v[106:109], v0 offset:34816
	ds_read_b128 v[110:113], v0 offset:36864
	ds_read_b128 v[114:117], v0 offset:38912
	v_add_u32_e32 v0, 0, v2
	s_addc_u32 s31, s47, 0
	ds_read_b128 v[118:121], v0 offset:49152
	ds_read_b128 v[122:125], v0 offset:51200
	ds_read_b128 v[126:129], v0 offset:53248
	ds_read_b128 v[130:133], v0 offset:55296
	s_add_u32 s36, s46, s36
	s_addc_u32 s37, s47, 0
	s_add_u32 s34, s30, 0x65a8000
	s_addc_u32 s35, s31, 0
	s_add_u32 s30, s36, 0xff9c000
	s_addc_u32 s31, s37, 0
	s_setprio 1
	s_waitcnt lgkmcnt(0)
	v_mfma_f32_16x16x32_bf16 v[56:59], v[98:101], v[68:71], v[56:59]
	v_mfma_f32_16x16x32_bf16 v[48:51], v[90:93], v[72:75], v[48:51]
	v_mfma_f32_16x16x32_bf16 v[44:47], v[94:97], v[72:75], v[44:47]
	v_mfma_f32_16x16x32_bf16 v[40:43], v[98:101], v[72:75], v[40:43]
	v_mfma_f32_16x16x32_bf16 v[36:39], v[102:105], v[72:75], v[36:39]
	v_mfma_f32_16x16x32_bf16 v[32:35], v[90:93], v[76:79], v[32:35]
	v_mfma_f32_16x16x32_bf16 v[28:31], v[94:97], v[76:79], v[28:31]
	v_mfma_f32_16x16x32_bf16 v[24:27], v[98:101], v[76:79], v[24:27]
	v_mfma_f32_16x16x32_bf16 v[20:23], v[102:105], v[76:79], v[20:23]
	v_mfma_f32_16x16x32_bf16 v[16:19], v[90:93], v[86:89], v[16:19]
	v_mfma_f32_16x16x32_bf16 v[12:15], v[94:97], v[86:89], v[12:15]
	v_mfma_f32_16x16x32_bf16 v[8:11], v[98:101], v[86:89], v[8:11]
	v_mfma_f32_16x16x32_bf16 v[4:7], v[102:105], v[86:89], v[4:7]
	v_mfma_f32_16x16x32_bf16 v[64:67], v[90:93], v[68:71], v[64:67]
	v_mfma_f32_16x16x32_bf16 v[60:63], v[94:97], v[68:71], v[60:63]
	v_mfma_f32_16x16x32_bf16 v[52:55], v[102:105], v[68:71], v[52:55]
	v_mfma_f32_16x16x32_bf16 v[56:59], v[126:129], v[80:83], v[56:59]
	v_mfma_f32_16x16x32_bf16 v[48:51], v[118:121], v[106:109], v[48:51]
	v_mfma_f32_16x16x32_bf16 v[44:47], v[122:125], v[106:109], v[44:47]
	v_mfma_f32_16x16x32_bf16 v[40:43], v[126:129], v[106:109], v[40:43]
	v_mfma_f32_16x16x32_bf16 v[36:39], v[130:133], v[106:109], v[36:39]
	v_mfma_f32_16x16x32_bf16 v[32:35], v[118:121], v[110:113], v[32:35]
	v_mfma_f32_16x16x32_bf16 v[28:31], v[122:125], v[110:113], v[28:31]
	v_mfma_f32_16x16x32_bf16 v[24:27], v[126:129], v[110:113], v[24:27]
	v_mfma_f32_16x16x32_bf16 v[20:23], v[130:133], v[110:113], v[20:23]
	v_mfma_f32_16x16x32_bf16 v[16:19], v[118:121], v[114:117], v[16:19]
	v_mfma_f32_16x16x32_bf16 v[12:15], v[122:125], v[114:117], v[12:15]
	v_mfma_f32_16x16x32_bf16 v[8:11], v[126:129], v[114:117], v[8:11]
	v_mfma_f32_16x16x32_bf16 v[4:7], v[130:133], v[114:117], v[4:7]
	v_mfma_f32_16x16x32_bf16 v[64:67], v[118:121], v[80:83], v[64:67]
	v_mfma_f32_16x16x32_bf16 v[60:63], v[122:125], v[80:83], v[60:63]
	v_mfma_f32_16x16x32_bf16 v[68:71], v[130:133], v[80:83], v[52:55]
	s_setprio 0
	v_mov_b32_e32 v0, v198
	s_waitcnt vmcnt(0) lgkmcnt(0)
	s_barrier
; __device__ __forceinline__ unsigned pk2(float lo, float hi) { unsigned r; asm("v_cvt_pk_bf16_f32 %0, %1, %2" : "=v"(r) : "v"(lo), "v"(hi)); return r; }
; __device__ __forceinline__ float bflo(unsigned u) { return __uint_as_float(u << 16); }
; __device__ __forceinline__ float bfhi(unsigned u) { return __uint_as_float(u & 0xffff0000u); }
; __device__ __forceinline__ void gemm_RES(const bf16_t* A, int K, const bf16_t* Bt, const float* xin, float* xout, bf16_t* xb, float* rss, int item, char* lds) {
;     ...
; #pragma unroll
;   for (int m = 0; m < 4; m++) {
;     const int rowg = m0 + wr * 64 + m * 16 + fr;
;     const size_t ro = (size_t)rowg * DM;
;     float sq = 0.f;
; #pragma unroll
;     for (int n = 0; n < 4; n++) {
;       const int col = n0 + wc * 64 + n * 16 + fq * 4;
;       f32x4 xv = *(const f32x4*)(xin + ro + col);
;       const f32x4 xn = xv + acc[m][n];
;       *(f32x4*)(xout + ro + col) = xn;
;       u32x2 w; w[0] = pk2(xn[0], xn[1]); w[1] = pk2(xn[2], xn[3]); *(u32x2*)(xb + ro + col) = w;
;       const float b0 = bflo(w[0]), b1 = bfhi(w[0]), b2 = bflo(w[1]), b3 = bfhi(w[1]);
;       sq += b0 * b0 + b1 * b1 + b2 * b2 + b3 * b3;
;     }
;     sq += __shfl_xor(sq, 16); sq += __shfl_xor(sq, 32);
;     if (fq == 0) unsafeAtomicAdd(rss + rowg, sq);
;   }
	v_readlane_b32 s4, v252, 35
	v_ashrrev_i32_e32 v2, 1, v0
	v_and_b32_e32 v2, 0xffffffc0, v2
	v_add_u32_e32 v2, s3, v2
	v_bfe_u32 v82, v0, 4, 2
	v_and_or_b32 v52, v0, 15, v2
	v_and_b32_e32 v1, 64, v0
	v_lshlrev_b32_e32 v0, 2, v82
	v_ashrrev_i32_e32 v53, 31, v52
	v_or3_b32 v78, v0, v1, s2
	v_lshlrev_b64 v[54:55], 12, v[52:53]
	v_lshl_add_u64 v[0:1], s[26:27], 0, v[54:55]
	v_lshlrev_b32_e32 v2, 2, v78
	v_lshl_add_u64 v[76:77], v[0:1], 0, v[2:3]
	global_load_dwordx4 v[72:75], v[76:77], off
	v_lshlrev_b32_e32 v0, 1, v78
	v_lshlrev_b64 v[78:79], 11, v[52:53]
	v_readlane_b32 s18, v252, 49
	v_readlane_b32 s19, v252, 50
	v_mov_b32_e32 v1, v3
	v_lshl_add_u64 v[78:79], s[34:35], 0, v[78:79]
	v_lshl_add_u64 v[54:55], s[18:19], 0, v[54:55]
	v_lshl_add_u64 v[80:81], v[54:55], 0, v[2:3]
	v_lshl_add_u64 v[78:79], v[78:79], 0, v[0:1]
	v_readlane_b32 s5, v252, 36
	v_readlane_b32 s6, v252, 37
	v_readlane_b32 s7, v252, 38
	v_readlane_b32 s8, v252, 39
	v_readlane_b32 s9, v252, 40
	v_readlane_b32 s10, v252, 41
	v_readlane_b32 s11, v252, 42
	v_readlane_b32 s12, v252, 43
	v_readlane_b32 s13, v252, 44
	v_readlane_b32 s14, v252, 45
	v_readlane_b32 s15, v252, 46
	v_readlane_b32 s16, v252, 47
	v_readlane_b32 s17, v252, 48
	s_waitcnt vmcnt(0)
	v_pk_add_f32 v[66:67], v[66:67], v[74:75]
	v_pk_add_f32 v[64:65], v[64:65], v[72:73]
	global_store_dwordx4 v[80:81], v[64:67], off
	v_cvt_pk_bf16_f32 v54, v64, v65
	v_cvt_pk_bf16_f32 v55, v66, v67
	global_store_dwordx2 v[78:79], v[54:55], off
	global_load_dwordx4 v[64:67], v[76:77], off offset:64
	s_waitcnt vmcnt(0)
	v_pk_add_f32 v[62:63], v[62:63], v[66:67]
	v_pk_add_f32 v[60:61], v[60:61], v[64:65]
	global_store_dwordx4 v[80:81], v[60:63], off offset:64
	v_cvt_pk_bf16_f32 v64, v60, v61
	v_cvt_pk_bf16_f32 v65, v62, v63
	global_store_dwordx2 v[78:79], v[64:65], off offset:32
	global_load_dwordx4 v[60:63], v[76:77], off offset:128
	v_lshlrev_b32_e32 v66, 16, v54
	v_and_b32_e32 v54, 0xffff0000, v54
	v_mul_f32_e32 v54, v54, v54
	v_lshlrev_b32_e32 v67, 16, v55
	v_fmac_f32_e32 v54, v66, v66
	v_and_b32_e32 v55, 0xffff0000, v55
	v_fmac_f32_e32 v54, v67, v67
	v_fmac_f32_e32 v54, v55, v55
	v_lshlrev_b32_e32 v55, 16, v64
	v_and_b32_e32 v64, 0xffff0000, v64
	v_mul_f32_e32 v64, v64, v64
	v_lshlrev_b32_e32 v66, 16, v65
	v_fmac_f32_e32 v64, v55, v55
	v_and_b32_e32 v65, 0xffff0000, v65
	v_fmac_f32_e32 v64, v66, v66
	v_fmac_f32_e32 v64, v65, v65
	v_add_f32_e32 v54, v54, v64
	s_waitcnt vmcnt(0)
	v_pk_add_f32 v[58:59], v[58:59], v[62:63]
	v_pk_add_f32 v[56:57], v[56:57], v[60:61]
	global_store_dwordx4 v[80:81], v[56:59], off offset:128
	v_cvt_pk_bf16_f32 v62, v56, v57
	v_cvt_pk_bf16_f32 v63, v58, v59
	global_store_dwordx2 v[78:79], v[62:63], off offset:64
	global_load_dwordx4 v[58:61], v[76:77], off offset:192
	v_lshlrev_b32_e32 v55, 16, v62
	v_and_b32_e32 v62, 0xffff0000, v62
	v_mul_f32_e32 v62, v62, v62
	v_lshlrev_b32_e32 v64, 16, v63
	v_fmac_f32_e32 v62, v55, v55
	v_and_b32_e32 v63, 0xffff0000, v63
	v_fmac_f32_e32 v62, v64, v64
	v_fmac_f32_e32 v62, v63, v63
	v_add_f32_e32 v54, v54, v62
	v_and_b32_e32 v57, 64, v218
	v_xor_b32_e32 v56, 16, v218
	v_add_u32_e32 v57, 64, v57
	v_cmp_lt_i32_e32 vcc, v56, v57
	s_waitcnt vmcnt(0)
	v_pk_add_f32 v[58:59], v[68:69], v[58:59]
	s_nop 0
	v_cvt_pk_bf16_f32 v62, v58, v59
	v_pk_add_f32 v[60:61], v[70:71], v[60:61]
	v_and_b32_e32 v64, 0xffff0000, v62
	v_lshlrev_b32_e32 v55, 16, v62
	v_mul_f32_e32 v64, v64, v64
	v_cvt_pk_bf16_f32 v63, v60, v61
	v_fmac_f32_e32 v64, v55, v55
	v_lshlrev_b32_e32 v65, 16, v63
	v_and_b32_e32 v66, 0xffff0000, v63
	v_fmac_f32_e32 v64, v65, v65
	v_cndmask_b32_e32 v56, v218, v56, vcc
	v_fmac_f32_e32 v64, v66, v66
	v_lshlrev_b32_e32 v56, 2, v56
	v_add_f32_e32 v54, v54, v64
	ds_bpermute_b32 v55, v56, v54
	v_xor_b32_e32 v64, 32, v218
	v_cmp_lt_i32_e32 vcc, v64, v57
	global_store_dwordx4 v[80:81], v[58:61], off offset:192
	global_store_dwordx2 v[78:79], v[62:63], off offset:96
	v_cndmask_b32_e32 v57, v218, v64, vcc
	s_waitcnt lgkmcnt(0)
	v_add_f32_e32 v54, v54, v55
	v_lshlrev_b32_e32 v57, 2, v57
	ds_bpermute_b32 v55, v57, v54
	v_cmp_eq_u32_e32 vcc, 0, v82
	s_and_saveexec_b64 s[36:37], vcc
	s_cbranch_execz .LBB0_129
	v_lshl_add_u64 v[58:59], v[52:53], 2, s[30:31]
	s_waitcnt lgkmcnt(0)
	v_add_f32_e32 v53, v54, v55
	global_atomic_add_f32 v[58:59], v53, off

; __device__ __forceinline__ void gemm_mainloop_d(const bf16_t* __restrict__ Ap, int lda, const bf16_t* __restrict__ Bt, int K,
;                                                 int m0, int n0, f32x4 (&acc)[4][4], char* lds) {
;     ...
;   auto dma = [&](int kt, int st) {
;     char* la = lds + st * 32768; char* lb = la + 16384;
; #pragma unroll
;     for (int i = 0; i < 4; i++) {
;       const int row = i * 32 + lrow; const int c = cph ^ ((row >> 1) & 7);
;       __builtin_amdgcn_global_load_lds((const unsigned*)(Ap + (size_t)(m0 + row) * lda + kt * 64 + c * 8), (__attribute__((address_space(3))) unsigned*)(la + i * 4096 + tid * 16), 16, 0, 0);
;       __builtin_amdgcn_global_load_lds((const unsigned*)(Bt + (size_t)(n0 + row) * K + kt * 64 + c * 8), (__attribute__((address_space(3))) unsigned*)(lb + i * 4096 + tid * 16), 16, 0, 0);
;     }
;   };
;   dma(0, 0);
;   asm volatile("s_waitcnt vmcnt(0)" ::: "memory"); __builtin_amdgcn_s_barrier(); asm volatile("" ::: "memory");
;   for (int kt = 0; kt < nk; kt++) {
;     const int st = kt & 1;
;     if (kt + 1 < nk) dma(kt + 1, st ^ 1);
;     const char* la = lds + st * 32768; const char* lb = la + 16384;
;     bf16x8 af[2][4], bfv[2][4];
; #pragma unroll
;     for (int kc = 0; kc < 2; kc++) {
; #pragma unroll
;       for (int m = 0; m < 4; m++) { const int row = wr * 64 + m * 16 + fr; af[kc][m] = *(const bf16x8*)(la + (row * 8 + ((kc * 4 + fq) ^ ((row >> 1) & 7))) * 16); }
; #pragma unroll
;       for (int n = 0; n < 4; n++) { const int row = wc * 64 + n * 16 + fr; bfv[kc][n] = *(const bf16x8*)(lb + (row * 8 + ((kc * 4 + fq) ^ ((row >> 1) & 7))) * 16); }
;     }
;     __builtin_amdgcn_s_setprio(1);
; #pragma unroll
;     for (int kc = 0; kc < 2; kc++)
; #pragma unroll
;       for (int m = 0; m < 4; m++)
; #pragma unroll
;         for (int n = 0; n < 4; n++) acc[m][n] = __builtin_amdgcn_mfma_f32_16x16x32_bf16(bfv[kc][n], af[kc][m], acc[m][n], 0, 0, 0);
;     __builtin_amdgcn_s_setprio(0);
;     asm volatile("s_waitcnt vmcnt(0) lgkmcnt(0)" ::: "memory"); __builtin_amdgcn_s_barrier(); asm volatile("" ::: "memory");
;   }
.LBB0_657:
	s_setprio 3
	s_and_b32 s28, s25, 0x8000
	s_xor_b32 s29, s28, 0x8000
	s_add_i32 s29, s29, vcc_hi
	s_mov_b32 m0, s29
	s_add_i32 vcc_lo, s29, 0x4000
	global_load_lds_dwordx4 v150, s[46:47]
	s_mov_b32 m0, vcc_lo
	s_add_i32 vcc_lo, s29, 0x1000
	global_load_lds_dwordx4 v151, s[46:47]
	s_mov_b32 m0, vcc_lo
	s_add_i32 vcc_lo, s29, 0x5000
	global_load_lds_dwordx4 v152, s[46:47]
	s_mov_b32 m0, vcc_lo
	s_add_i32 vcc_lo, s29, 0x2000
	global_load_lds_dwordx4 v153, s[46:47]
	s_mov_b32 m0, vcc_lo
	s_add_i32 vcc_lo, s29, 0x6000
	global_load_lds_dwordx4 v154, s[46:47]
	s_mov_b32 m0, vcc_lo
	s_add_i32 vcc_lo, s29, 0x3000
	global_load_lds_dwordx4 v155, s[46:47]
	s_mov_b32 m0, vcc_lo
	s_add_i32 vcc_lo, s29, 0x7000
	global_load_lds_dwordx4 v156, s[46:47]
	s_mov_b32 m0, vcc_lo
	s_nop 0
	global_load_lds_dwordx4 v157, s[46:47]
	v_add_u32_e32 v150, 0x80, v150
	v_add_u32_e32 v151, 0x80, v151
	v_add_u32_e32 v152, 0x80, v152
	v_add_u32_e32 v153, 0x80, v153
	v_add_u32_e32 v154, 0x80, v154
	v_add_u32_e32 v155, 0x80, v155
	v_add_u32_e32 v156, 0x80, v156
	v_add_u32_e32 v157, 0x80, v157
	v_add_u32_e32 v98, s28, v85
	v_add_u32_e32 v114, s28, v84
	v_add_u32_e32 v130, s28, v83
	v_add_u32_e32 v146, s28, v2
	ds_read_b128 v[86:89], v98
	ds_read_b128 v[90:93], v98 offset:2048
	ds_read_b128 v[94:97], v98 offset:4096
	ds_read_b128 v[98:101], v98 offset:6144
	ds_read_b128 v[102:105], v114 offset:16384
	ds_read_b128 v[106:109], v114 offset:18432
	ds_read_b128 v[110:113], v114 offset:20480
	ds_read_b128 v[114:117], v114 offset:22528
	ds_read_b128 v[118:121], v130
	ds_read_b128 v[122:125], v130 offset:2048
	ds_read_b128 v[126:129], v130 offset:4096
	ds_read_b128 v[130:133], v130 offset:6144
	ds_read_b128 v[134:137], v146 offset:16384
	ds_read_b128 v[138:141], v146 offset:18432
	ds_read_b128 v[142:145], v146 offset:20480
	ds_read_b128 v[146:149], v146 offset:22528
	s_setprio 1
	s_waitcnt lgkmcnt(0)
	v_mfma_f32_16x16x32_bf16 v[64:67], v[102:105], v[86:89], v[64:67]
	v_mfma_f32_16x16x32_bf16 v[60:63], v[106:109], v[86:89], v[60:63]
	v_mfma_f32_16x16x32_bf16 v[56:59], v[110:113], v[86:89], v[56:59]
	v_mfma_f32_16x16x32_bf16 v[52:55], v[114:117], v[86:89], v[52:55]
	v_mfma_f32_16x16x32_bf16 v[48:51], v[102:105], v[90:93], v[48:51]
	v_mfma_f32_16x16x32_bf16 v[44:47], v[106:109], v[90:93], v[44:47]
	v_mfma_f32_16x16x32_bf16 v[40:43], v[110:113], v[90:93], v[40:43]
	v_mfma_f32_16x16x32_bf16 v[36:39], v[114:117], v[90:93], v[36:39]
	v_mfma_f32_16x16x32_bf16 v[32:35], v[102:105], v[94:97], v[32:35]
	v_mfma_f32_16x16x32_bf16 v[28:31], v[106:109], v[94:97], v[28:31]
	v_mfma_f32_16x16x32_bf16 v[24:27], v[110:113], v[94:97], v[24:27]
	v_mfma_f32_16x16x32_bf16 v[20:23], v[114:117], v[94:97], v[20:23]
	v_mfma_f32_16x16x32_bf16 v[16:19], v[102:105], v[98:101], v[16:19]
	v_mfma_f32_16x16x32_bf16 v[12:15], v[106:109], v[98:101], v[12:15]
	v_mfma_f32_16x16x32_bf16 v[8:11], v[110:113], v[98:101], v[8:11]
	v_mfma_f32_16x16x32_bf16 v[4:7], v[114:117], v[98:101], v[4:7]
	v_mfma_f32_16x16x32_bf16 v[64:67], v[134:137], v[118:121], v[64:67]
	v_mfma_f32_16x16x32_bf16 v[60:63], v[138:141], v[118:121], v[60:63]
	v_mfma_f32_16x16x32_bf16 v[56:59], v[142:145], v[118:121], v[56:59]
	v_mfma_f32_16x16x32_bf16 v[52:55], v[146:149], v[118:121], v[52:55]
	v_mfma_f32_16x16x32_bf16 v[48:51], v[134:137], v[122:125], v[48:51]
	v_mfma_f32_16x16x32_bf16 v[44:47], v[138:141], v[122:125], v[44:47]
	v_mfma_f32_16x16x32_bf16 v[40:43], v[142:145], v[122:125], v[40:43]
	v_mfma_f32_16x16x32_bf16 v[36:39], v[146:149], v[122:125], v[36:39]
	v_mfma_f32_16x16x32_bf16 v[32:35], v[134:137], v[126:129], v[32:35]
	v_mfma_f32_16x16x32_bf16 v[28:31], v[138:141], v[126:129], v[28:31]
	v_mfma_f32_16x16x32_bf16 v[24:27], v[142:145], v[126:129], v[24:27]
	v_mfma_f32_16x16x32_bf16 v[20:23], v[146:149], v[126:129], v[20:23]
	v_mfma_f32_16x16x32_bf16 v[16:19], v[134:137], v[130:133], v[16:19]
	v_mfma_f32_16x16x32_bf16 v[12:15], v[138:141], v[130:133], v[12:15]
	v_mfma_f32_16x16x32_bf16 v[8:11], v[142:145], v[130:133], v[8:11]
	v_mfma_f32_16x16x32_bf16 v[4:7], v[146:149], v[130:133], v[4:7]
	s_setprio 0
	s_waitcnt vmcnt(0) lgkmcnt(0)
	s_barrier
	s_add_u32 s26, s26, 0x80
	s_addc_u32 s27, s27, 0
	s_add_i32 s25, s25, 0x8000
	s_cmpk_eq_i32 s26, 0x780
	s_cbranch_scc0 .LBB0_657
; __device__ __forceinline__ unsigned char* WS(const Params& p) { unsigned z = 0; asm volatile("" : "+s"(z)); return p.ws + z; }
; __device__ __forceinline__ unsigned pk2(float lo, float hi) { unsigned r; asm("v_cvt_pk_bf16_f32 %0, %1, %2" : "=v"(r) : "v"(lo), "v"(hi)); return r; }
; __device__ __forceinline__ float bflo(unsigned u) { return __uint_as_float(u << 16); }
; __device__ __forceinline__ void gemm_mainloop_d(const bf16_t* __restrict__ Ap, int lda, const bf16_t* __restrict__ Bt, int K,
;                                                 int m0, int n0, f32x4 (&acc)[4][4], char* lds) {
;     ...
;     const char* la = lds + st * 32768; const char* lb = la + 16384;
;     bf16x8 af[2][4], bfv[2][4];
; #pragma unroll
;     for (int kc = 0; kc < 2; kc++) {
; #pragma unroll
;       for (int m = 0; m < 4; m++) { const int row = wr * 64 + m * 16 + fr; af[kc][m] = *(const bf16x8*)(la + (row * 8 + ((kc * 4 + fq) ^ ((row >> 1) & 7))) * 16); }
; #pragma unroll
;       for (int n = 0; n < 4; n++) { const int row = wc * 64 + n * 16 + fr; bfv[kc][n] = *(const bf16x8*)(lb + (row * 8 + ((kc * 4 + fq) ^ ((row >> 1) & 7))) * 16); }
;     }
;     __builtin_amdgcn_s_setprio(1);
; #pragma unroll
;     for (int kc = 0; kc < 2; kc++)
; #pragma unroll
;       for (int m = 0; m < 4; m++)
; #pragma unroll
;         for (int n = 0; n < 4; n++) acc[m][n] = __builtin_amdgcn_mfma_f32_16x16x32_bf16(bfv[kc][n], af[kc][m], acc[m][n], 0, 0, 0);
;     __builtin_amdgcn_s_setprio(0);
;     asm volatile("s_waitcnt vmcnt(0) lgkmcnt(0)" ::: "memory"); __builtin_amdgcn_s_barrier(); asm volatile("" ::: "memory");
;   }
; __device__ __forceinline__ void gemm_A(const Params& p, int item, char* lds) {
;     ...
;   const float* rssg = (const float*)(WS(p) + OFF_RSS) + m0;
;   bf16_t* P = (bf16_t*)(WS(p) + OFF_P);
; #pragma unroll
;   for (int m = 0; m < 4; m++) {
;     const int rl = wr * 64 + m * 16 + fr; const float r = rsqrtf(rssg[rl] * (1.f / 1024.f) + 1e-6f);
;     float sq = 0.f;
; #pragma unroll
;     for (int n = 0; n < 4; n++) {
;       const int col = n0 + wc * 64 + n * 16 + fq * 4;
;       if (col < PIN) { f32x4 v = acc[m][n] * r; u32x2 w; w[0] = pk2(v[0], v[1]); w[1] = pk2(v[2], v[3]); *(u32x2*)(P + (size_t)(m0 + rl) * PIN + col) = w;
;         const float b0 = bflo(w[0]), b1 = bfhi(w[0]), b2 = bflo(w[1]), b3 = bfhi(w[1]); sq += b0 * b0 + b1 * b1 + b2 * b2 + b3 * b3; }
	v_add_u32_e32 v0, 0, v85
	ds_read_b128 v[68:71], v0 offset:32768
	ds_read_b128 v[72:75], v0 offset:34816
	ds_read_b128 v[76:79], v0 offset:36864
	ds_read_b128 v[86:89], v0 offset:38912
	v_add_u32_e32 v0, 0, v84
	ds_read_b128 v[90:93], v0 offset:49152
	ds_read_b128 v[94:97], v0 offset:51200
	ds_read_b128 v[98:101], v0 offset:53248
	ds_read_b128 v[102:105], v0 offset:55296
	v_add_u32_e32 v0, 0, v83
	ds_read_b128 v[80:83], v0 offset:32768
	ds_read_b128 v[106:109], v0 offset:34816
	ds_read_b128 v[110:113], v0 offset:36864
	ds_read_b128 v[114:117], v0 offset:38912
	v_add_u32_e32 v0, 0, v2
	ds_read_b128 v[118:121], v0 offset:49152
	ds_read_b128 v[122:125], v0 offset:51200
	ds_read_b128 v[126:129], v0 offset:53248
	ds_read_b128 v[130:133], v0 offset:55296
	s_setprio 1
	s_waitcnt lgkmcnt(0)
	v_mfma_f32_16x16x32_bf16 v[64:67], v[90:93], v[68:71], v[64:67]
	v_mfma_f32_16x16x32_bf16 v[60:63], v[94:97], v[68:71], v[60:63]
	v_mfma_f32_16x16x32_bf16 v[56:59], v[98:101], v[68:71], v[56:59]
	v_mfma_f32_16x16x32_bf16 v[52:55], v[102:105], v[68:71], v[52:55]
	v_mfma_f32_16x16x32_bf16 v[48:51], v[90:93], v[72:75], v[48:51]
	v_mfma_f32_16x16x32_bf16 v[44:47], v[94:97], v[72:75], v[44:47]
	v_mfma_f32_16x16x32_bf16 v[40:43], v[98:101], v[72:75], v[40:43]
	v_mfma_f32_16x16x32_bf16 v[36:39], v[102:105], v[72:75], v[36:39]
	v_mfma_f32_16x16x32_bf16 v[32:35], v[90:93], v[76:79], v[32:35]
	v_mfma_f32_16x16x32_bf16 v[28:31], v[94:97], v[76:79], v[28:31]
	v_mfma_f32_16x16x32_bf16 v[24:27], v[98:101], v[76:79], v[24:27]
	v_mfma_f32_16x16x32_bf16 v[20:23], v[102:105], v[76:79], v[20:23]
	v_mfma_f32_16x16x32_bf16 v[16:19], v[90:93], v[86:89], v[16:19]
	v_mfma_f32_16x16x32_bf16 v[12:15], v[94:97], v[86:89], v[12:15]
	v_mfma_f32_16x16x32_bf16 v[8:11], v[98:101], v[86:89], v[8:11]
	v_mfma_f32_16x16x32_bf16 v[4:7], v[102:105], v[86:89], v[4:7]
	v_mfma_f32_16x16x32_bf16 v[64:67], v[118:121], v[80:83], v[64:67]
	v_mfma_f32_16x16x32_bf16 v[60:63], v[122:125], v[80:83], v[60:63]
	v_mfma_f32_16x16x32_bf16 v[56:59], v[126:129], v[80:83], v[56:59]
	v_mfma_f32_16x16x32_bf16 v[52:55], v[130:133], v[80:83], v[52:55]
	v_mfma_f32_16x16x32_bf16 v[48:51], v[118:121], v[106:109], v[48:51]
	v_mfma_f32_16x16x32_bf16 v[44:47], v[122:125], v[106:109], v[44:47]
	v_mfma_f32_16x16x32_bf16 v[40:43], v[126:129], v[106:109], v[40:43]
	v_mfma_f32_16x16x32_bf16 v[36:39], v[130:133], v[106:109], v[36:39]
	v_mfma_f32_16x16x32_bf16 v[32:35], v[118:121], v[110:113], v[32:35]
	v_mfma_f32_16x16x32_bf16 v[28:31], v[122:125], v[110:113], v[28:31]
	v_mfma_f32_16x16x32_bf16 v[24:27], v[126:129], v[110:113], v[24:27]
	v_mfma_f32_16x16x32_bf16 v[20:23], v[130:133], v[110:113], v[20:23]
	v_mfma_f32_16x16x32_bf16 v[16:19], v[118:121], v[114:117], v[16:19]
	v_mfma_f32_16x16x32_bf16 v[12:15], v[122:125], v[114:117], v[12:15]
	v_mfma_f32_16x16x32_bf16 v[8:11], v[126:129], v[114:117], v[8:11]
	v_mfma_f32_16x16x32_bf16 v[4:7], v[130:133], v[114:117], v[4:7]
	s_setprio 0
	v_mov_b32_e32 v2, v198
	s_mov_b32 s25, s89
	s_waitcnt vmcnt(0) lgkmcnt(0)
	s_barrier
	s_add_u32 s28, s46, s25
	s_addc_u32 s29, s47, 0
	s_ashr_i32 s25, s24, 31
	v_and_b32_e32 v0, 15, v2
	s_lshl_b64 s[26:27], s[24:25], 2
	v_ashrrev_i32_e32 v1, 1, v2
	s_movk_i32 s4, 0xffc0
	s_add_u32 s28, s28, s26
	v_and_or_b32 v0, v1, s4, v0
	s_addc_u32 s29, s29, s27
	v_ashrrev_i32_e32 v1, 31, v0
	v_lshl_add_u64 v[70:71], v[0:1], 2, s[28:29]
	s_mov_b32 s28, 0xff8c000
	v_add_co_u32_e32 v68, vcc, s28, v70
	s_mov_b32 s25, s89
	s_nop 0
	v_addc_co_u32_e32 v69, vcc, 0, v71, vcc
	global_load_dword v69, v[68:69], off
	v_and_b32_e32 v68, 64, v2
	v_bfe_u32 v2, v2, 4, 2
	v_lshlrev_b32_e32 v72, 2, v2
	v_or3_b32 v68, v72, v68, s3
	s_add_u32 s3, s46, s25
	s_addc_u32 s25, s47, 0
	s_add_u32 s30, s3, 0x768000
	s_addc_u32 s31, s25, 0
	v_add_u32_e32 v74, s24, v0
	v_mov_b32_e32 v76, 0
	v_cmp_gt_i32_e64 s[34:35], s78, v68
	s_waitcnt vmcnt(0)
	v_fmamk_f32 v69, v69, 0x3a800000, v200
	v_mul_f32_e32 v72, 0x4b800000, v69
	v_cmp_gt_f32_e32 vcc, s83, v69
	s_nop 1
	v_cndmask_b32_e32 v69, v69, v72, vcc
	v_rsq_f32_e32 v69, v69
	v_mov_b64_e32 v[72:73], s[30:31]
	v_mad_i64_i32 v[72:73], s[28:29], v74, s69, v[72:73]
	v_mul_f32_e32 v74, 0x45800000, v69
	v_cndmask_b32_e32 v74, v69, v74, vcc
	v_mov_b32_e32 v75, v74
	v_ashrrev_i32_e32 v69, 31, v68
	s_and_saveexec_b64 s[28:29], s[34:35]
	s_cbranch_execz .LBB0_660
	v_mov_b32_e32 v76, v74
	v_mov_b32_e32 v77, v74
	v_pk_mul_f32 v[66:67], v[66:67], v[76:77]
	v_pk_mul_f32 v[64:65], v[64:65], v[74:75]
	s_nop 0
	v_cvt_pk_bf16_f32 v64, v64, v65
	v_cvt_pk_bf16_f32 v65, v66, v67
	v_lshl_add_u64 v[66:67], v[68:69], 1, v[72:73]
	global_store_dwordx2 v[66:67], v[64:65], off
	v_lshlrev_b32_e32 v66, 16, v64
	v_and_b32_e32 v67, 0xffff0000, v64
	v_pk_mul_f32 v[66:67], v[66:67], v[66:67]
	v_and_b32_e32 v64, 0xffff0000, v65
	v_lshlrev_b32_e32 v65, 16, v65
	v_pk_mul_f32 v[64:65], v[64:65], v[64:65]
	v_add_f32_e32 v66, v66, v67
	v_add_f32_e32 v65, v66, v65
	v_add_f32_e32 v76, v64, v65
